# same as previous best plus bounded outstanding-VMEM counts in the hand-written GLA-prep phase (robustness: vmcnt never above 60)
# speedup vs baseline: 1.0677x; 1.0015x over previous
; DI float bf2f(bf16_t v) { return __uint_as_float(((unsigned)v) << 16); }
; DI void phase_gla_prep(const Params& p, int g, char* smem, int bid, int nb) {
;     ...
;   for (int item = bid; item < 2048; item += nb) {
;     const int c = item & 255, head = (item >> 8) & 3, dir = item >> 10, dd = head * 128 + d;
;     __syncthreads();
; #pragma unroll
;     for (int i = 0; i < 4; ++i) { const int idx = tid + 256 * i; lrs[idx] = lrb[(size_t)(c * 64 + (idx >> 4)) * 32 + dir * 16 + (idx & 15)]; }
;     const float* wgp = dir ? p.w_gate_b : p.w_gate_f;
;     float wg[16];
; #pragma unroll
;     for (int r = 0; r < 16; ++r) wg[r] = wgp[r * 512 + dd];
;     const float bg = (dir ? p.b_gate_b : p.b_gate_f)[dd];
;     __syncthreads();
;     ...
;       const float qv = bf2f(proj[tg * NPROJ + PQG + dd]), kv = bf2f(proj[tg * NPROJ + PKG + dd]);
.Lgp_loop:
	s_and_b32 s10, s12, 0xff
	s_bfe_u32 s11, s12, 0x20008
	s_lshr_b32 s13, s12, 10
	s_lshl_b32 s0, s13, 2
	s_add_i32 s0, s0, s11
	s_lshl_b32 s0, s0, 8
	s_add_i32 s9, s0, s10
	v_readlane_b32 s16, v233, 26
	v_readlane_b32 s17, v233, 27
	s_lshl_b32 s0, s10, 13
	s_lshl_b32 s1, s13, 6
	s_add_i32 s0, s0, s1
	s_nop 1
	s_add_u32 s16, s16, s0
	s_addc_u32 s17, s17, 0
	v_readlane_b32 s18, v235, 29
	v_readlane_b32 s19, v235, 30
	v_readlane_b32 s0, v235, 33
	v_readlane_b32 s1, v235, 34
	v_readlane_b32 s20, v235, 31
	v_readlane_b32 s21, v235, 32
	v_readlane_b32 s22, v235, 35
	v_readlane_b32 s23, v235, 36
	s_nop 1
	s_cmp_eq_u32 s13, 0
	s_cselect_b32 s18, s18, s0
	s_cselect_b32 s19, s19, s1
	s_cselect_b32 s20, s20, s22
	s_cselect_b32 s21, s21, s23
	s_cselect_b64 s[6:7], -1, 0
	s_lshl_b32 s0, s11, 9
	s_add_u32 s18, s18, s0
	s_addc_u32 s19, s19, 0
	s_add_u32 s20, s20, s0
	s_addc_u32 s21, s21, 0
	s_mul_i32 s0, s10, 0xa0000
	s_lshl_b32 s1, s11, 8
	s_add_i32 s0, s0, s1
	s_add_u32 s22, s94, s0
	s_addc_u32 s23, s95, 0
	s_lshl_b32 s0, s9, 14
	s_add_u32 s24, s4, s0
	s_addc_u32 s25, s5, 0
	s_add_u32 s26, s68, s0
	s_addc_u32 s27, s69, 0
	v_readlane_b32 s28, v233, 20
	v_readlane_b32 s29, v233, 21
	v_readlane_b32 s30, v233, 22
	v_readlane_b32 s31, v233, 23
	s_nop 1
	s_add_u32 s28, s28, s0
	s_addc_u32 s29, s29, 0
	s_lshl_b32 s0, s9, 9
	s_add_u32 s30, s30, s0
	s_addc_u32 s31, s31, 0
	s_waitcnt vmcnt(8) lgkmcnt(0)
	s_barrier
	global_load_dword v33, v7, s[16:17]
	global_load_dword v34, v7, s[16:17] offset:2048
	global_load_dword v35, v8, s[16:17]
	global_load_dword v36, v8, s[16:17] offset:2048
	global_load_dword v16, v9, s[18:19]
	global_load_dword v17, v9, s[18:19] offset:2048
	s_add_u32 s18, s18, 0x1000
	s_addc_u32 s19, s19, 0
	global_load_dword v18, v9, s[18:19]
	global_load_dword v19, v9, s[18:19] offset:2048
	s_add_u32 s18, s18, 0x1000
	s_addc_u32 s19, s19, 0
	global_load_dword v20, v9, s[18:19]
	global_load_dword v21, v9, s[18:19] offset:2048
	s_add_u32 s18, s18, 0x1000
	s_addc_u32 s19, s19, 0
	global_load_dword v22, v9, s[18:19]
	global_load_dword v23, v9, s[18:19] offset:2048
	s_add_u32 s18, s18, 0x1000
	s_addc_u32 s19, s19, 0
	global_load_dword v24, v9, s[18:19]
	global_load_dword v25, v9, s[18:19] offset:2048
	s_add_u32 s18, s18, 0x1000
	s_addc_u32 s19, s19, 0
	global_load_dword v26, v9, s[18:19]
	global_load_dword v27, v9, s[18:19] offset:2048
	s_add_u32 s18, s18, 0x1000
	s_addc_u32 s19, s19, 0
	global_load_dword v28, v9, s[18:19]
	global_load_dword v29, v9, s[18:19] offset:2048
	s_add_u32 s18, s18, 0x1000
	s_addc_u32 s19, s19, 0
	global_load_dword v30, v9, s[18:19]
	global_load_dword v31, v9, s[18:19] offset:2048
	global_load_dword v32, v9, s[20:21]
	global_load_ushort v96, v4, s[22:23]
	global_load_ushort v144, v4, s[22:23] offset:1024
	s_add_u32 s22, s22, 0x2800
	s_addc_u32 s23, s23, 0
	global_load_ushort v97, v4, s[22:23]
	global_load_ushort v145, v4, s[22:23] offset:1024
	s_add_u32 s22, s22, 0x2800
	s_addc_u32 s23, s23, 0
	global_load_ushort v98, v4, s[22:23]
	global_load_ushort v146, v4, s[22:23] offset:1024
	s_add_u32 s22, s22, 0x2800
	s_addc_u32 s23, s23, 0
	global_load_ushort v99, v4, s[22:23]
	global_load_ushort v147, v4, s[22:23] offset:1024
	s_add_u32 s22, s22, 0x2800
	s_addc_u32 s23, s23, 0
	global_load_ushort v100, v4, s[22:23]
	global_load_ushort v148, v4, s[22:23] offset:1024
	s_add_u32 s22, s22, 0x2800
	s_addc_u32 s23, s23, 0
	global_load_ushort v101, v4, s[22:23]
	global_load_ushort v149, v4, s[22:23] offset:1024
	s_add_u32 s22, s22, 0x2800
	s_addc_u32 s23, s23, 0
	global_load_ushort v102, v4, s[22:23]
	global_load_ushort v150, v4, s[22:23] offset:1024
	s_add_u32 s22, s22, 0x2800
	s_addc_u32 s23, s23, 0
	global_load_ushort v103, v4, s[22:23]
	global_load_ushort v151, v4, s[22:23] offset:1024
	s_add_u32 s22, s22, 0x2800
	s_addc_u32 s23, s23, 0
	global_load_ushort v104, v4, s[22:23]
	global_load_ushort v152, v4, s[22:23] offset:1024
	s_add_u32 s22, s22, 0x2800
	s_addc_u32 s23, s23, 0
	global_load_ushort v105, v4, s[22:23]
	global_load_ushort v153, v4, s[22:23] offset:1024
	s_add_u32 s22, s22, 0x2800
	s_addc_u32 s23, s23, 0
	global_load_ushort v106, v4, s[22:23]
	global_load_ushort v154, v4, s[22:23] offset:1024
	s_add_u32 s22, s22, 0x2800
	s_addc_u32 s23, s23, 0
	global_load_ushort v107, v4, s[22:23]
	global_load_ushort v155, v4, s[22:23] offset:1024
	s_add_u32 s22, s22, 0x2800
	s_addc_u32 s23, s23, 0
	global_load_ushort v108, v4, s[22:23]
	global_load_ushort v156, v4, s[22:23] offset:1024
	s_add_u32 s22, s22, 0x2800
	s_addc_u32 s23, s23, 0
	global_load_ushort v109, v4, s[22:23]
	global_load_ushort v157, v4, s[22:23] offset:1024
	s_add_u32 s22, s22, 0x2800
	s_addc_u32 s23, s23, 0
	global_load_ushort v110, v4, s[22:23]
	global_load_ushort v158, v4, s[22:23] offset:1024
	s_add_u32 s22, s22, 0x2800
	s_addc_u32 s23, s23, 0
	global_load_ushort v111, v4, s[22:23]
	global_load_ushort v159, v4, s[22:23] offset:1024
	s_add_u32 s22, s22, 0x2800
	s_addc_u32 s23, s23, 0
	s_waitcnt vmcnt(49)
	ds_write_b32 v1, v33
	ds_write_b32 v1, v34 offset:1024
	ds_write_b32 v1, v35 offset:2048
	ds_write_b32 v1, v36 offset:3072
	s_waitcnt lgkmcnt(0)
	s_barrier
; DI float logsig16(float z) { return (fminf(z, 0.f) - __logf(1.f + __expf(-fabsf(z)))) * (1.f / 16.f); }
; DI void phase_gla_prep(const Params& p, int g, char* smem, int bid, int nb) {
;     ...
;     float tsum = 0.f;
;     for (int tt = 0; tt < 32; ++tt) {
;       const float* l = lrs + (half * 32 + tt) * 16; float z = bg;
; #pragma unroll
;       for (int r = 0; r < 16; ++r) z += l[r] * wg[r];
;       tsum += logsig16(z);
;     }
;     tot[half * 128 + d] = tsum;
	v_mov_b32_e32 v54, 0
	ds_read_b128 v[36:39], v2
	ds_read_b128 v[40:43], v2 offset:16
	ds_read_b128 v[44:47], v2 offset:32
	ds_read_b128 v[48:51], v2 offset:48
	ds_read_b128 v[176:179], v2 offset:64
	ds_read_b128 v[180:183], v2 offset:80
	ds_read_b128 v[184:187], v2 offset:96
	ds_read_b128 v[188:191], v2 offset:112
	s_waitcnt vmcnt(32)
	s_waitcnt lgkmcnt(4)
	v_fma_f32 v52, v16, v36, v32
	v_fmac_f32_e32 v52, v17, v37
	v_fmac_f32_e32 v52, v18, v38
	v_fmac_f32_e32 v52, v19, v39
	v_fmac_f32_e32 v52, v20, v40
	v_fmac_f32_e32 v52, v21, v41
	v_fmac_f32_e32 v52, v22, v42
	v_fmac_f32_e32 v52, v23, v43
	v_fmac_f32_e32 v52, v24, v44
	v_fmac_f32_e32 v52, v25, v45
	v_fmac_f32_e32 v52, v26, v46
	v_fmac_f32_e32 v52, v27, v47
	v_fmac_f32_e32 v52, v28, v48
	v_fmac_f32_e32 v52, v29, v49
	v_fmac_f32_e32 v52, v30, v50
	v_fmac_f32_e32 v52, v31, v51
	ds_read_b128 v[36:39], v2 offset:128
	ds_read_b128 v[40:43], v2 offset:144
	ds_read_b128 v[44:47], v2 offset:160
	ds_read_b128 v[48:51], v2 offset:176
	s_waitcnt lgkmcnt(4)
	v_fma_f32 v53, v16, v176, v32
	v_mul_f32_e64 v55, |v52|, s85
	v_fmac_f32_e32 v53, v17, v177
	v_exp_f32_e32 v55, v55
	v_fmac_f32_e32 v53, v18, v178
	v_min_f32_e32 v56, 0, v52
	v_fmac_f32_e32 v53, v19, v179
	v_add_f32_e32 v55, 1.0, v55
	v_fmac_f32_e32 v53, v20, v180
	v_log_f32_e32 v55, v55
	v_fmac_f32_e32 v53, v21, v181
	v_fmac_f32_e32 v53, v22, v182
	v_mul_f32_e32 v57, 0x3f317217, v55
	v_fmac_f32_e32 v53, v23, v183
	v_fma_f32 v58, v55, s74, -v57
	v_fmac_f32_e32 v53, v24, v184
	v_fmac_f32_e32 v58, 0x3377d1cf, v55
	v_fmac_f32_e32 v53, v25, v185
	v_fmac_f32_e32 v58, 0x3f317217, v55
	v_fmac_f32_e32 v53, v26, v186
	v_sub_f32_e32 v56, v56, v58
	v_fmac_f32_e32 v53, v27, v187
	v_mul_f32_e32 v64, 0x3d800000, v56
	v_fmac_f32_e32 v53, v28, v188
	v_add_f32_e32 v54, v54, v64
	v_fmac_f32_e32 v53, v29, v189
	v_fmac_f32_e32 v53, v30, v190
	v_fmac_f32_e32 v53, v31, v191
	ds_read_b128 v[176:179], v2 offset:192
	ds_read_b128 v[180:183], v2 offset:208
	ds_read_b128 v[184:187], v2 offset:224
	ds_read_b128 v[188:191], v2 offset:240
	s_waitcnt lgkmcnt(4)
	v_fma_f32 v52, v16, v36, v32
	v_mul_f32_e64 v55, |v53|, s85
	v_fmac_f32_e32 v52, v17, v37
	v_exp_f32_e32 v55, v55
	v_fmac_f32_e32 v52, v18, v38
	v_min_f32_e32 v56, 0, v53
	v_fmac_f32_e32 v52, v19, v39
	v_add_f32_e32 v55, 1.0, v55
	v_fmac_f32_e32 v52, v20, v40
	v_log_f32_e32 v55, v55
	v_fmac_f32_e32 v52, v21, v41
	v_fmac_f32_e32 v52, v22, v42
	v_mul_f32_e32 v57, 0x3f317217, v55
	v_fmac_f32_e32 v52, v23, v43
	v_fma_f32 v58, v55, s74, -v57
	v_fmac_f32_e32 v52, v24, v44
	v_fmac_f32_e32 v58, 0x3377d1cf, v55
	v_fmac_f32_e32 v52, v25, v45
	v_fmac_f32_e32 v58, 0x3f317217, v55
	v_fmac_f32_e32 v52, v26, v46
	v_sub_f32_e32 v56, v56, v58
	v_fmac_f32_e32 v52, v27, v47
	v_mul_f32_e32 v65, 0x3d800000, v56
	v_fmac_f32_e32 v52, v28, v48
	v_add_f32_e32 v54, v54, v65
	v_fmac_f32_e32 v52, v29, v49
	v_fmac_f32_e32 v52, v30, v50
	v_fmac_f32_e32 v52, v31, v51
	ds_read_b128 v[36:39], v2 offset:256
	ds_read_b128 v[40:43], v2 offset:272
	ds_read_b128 v[44:47], v2 offset:288
	ds_read_b128 v[48:51], v2 offset:304
	s_waitcnt lgkmcnt(4)
	v_fma_f32 v53, v16, v176, v32
	v_mul_f32_e64 v55, |v52|, s85
	v_fmac_f32_e32 v53, v17, v177
	v_exp_f32_e32 v55, v55
	v_fmac_f32_e32 v53, v18, v178
	v_min_f32_e32 v56, 0, v52
	v_fmac_f32_e32 v53, v19, v179
	v_add_f32_e32 v55, 1.0, v55
	v_fmac_f32_e32 v53, v20, v180
	v_log_f32_e32 v55, v55
	v_fmac_f32_e32 v53, v21, v181
	v_fmac_f32_e32 v53, v22, v182
	v_mul_f32_e32 v57, 0x3f317217, v55
	v_fmac_f32_e32 v53, v23, v183
	v_fma_f32 v58, v55, s74, -v57
	v_fmac_f32_e32 v53, v24, v184
	v_fmac_f32_e32 v58, 0x3377d1cf, v55
	v_fmac_f32_e32 v53, v25, v185
	v_fmac_f32_e32 v58, 0x3f317217, v55
	v_fmac_f32_e32 v53, v26, v186
	v_sub_f32_e32 v56, v56, v58
	v_fmac_f32_e32 v53, v27, v187
	v_mul_f32_e32 v66, 0x3d800000, v56
	v_fmac_f32_e32 v53, v28, v188
	v_add_f32_e32 v54, v54, v66
	v_fmac_f32_e32 v53, v29, v189
	v_fmac_f32_e32 v53, v30, v190
	v_fmac_f32_e32 v53, v31, v191
	ds_read_b128 v[176:179], v2 offset:320
	ds_read_b128 v[180:183], v2 offset:336
	ds_read_b128 v[184:187], v2 offset:352
	ds_read_b128 v[188:191], v2 offset:368
	s_waitcnt lgkmcnt(4)
	v_fma_f32 v52, v16, v36, v32
	v_mul_f32_e64 v55, |v53|, s85
	v_fmac_f32_e32 v52, v17, v37
	v_exp_f32_e32 v55, v55
	v_fmac_f32_e32 v52, v18, v38
	v_min_f32_e32 v56, 0, v53
	v_fmac_f32_e32 v52, v19, v39
	v_add_f32_e32 v55, 1.0, v55
	v_fmac_f32_e32 v52, v20, v40
	v_log_f32_e32 v55, v55
	v_fmac_f32_e32 v52, v21, v41
	v_fmac_f32_e32 v52, v22, v42
	v_mul_f32_e32 v57, 0x3f317217, v55
	v_fmac_f32_e32 v52, v23, v43
	v_fma_f32 v58, v55, s74, -v57
	v_fmac_f32_e32 v52, v24, v44
	v_fmac_f32_e32 v58, 0x3377d1cf, v55
	v_fmac_f32_e32 v52, v25, v45
	v_fmac_f32_e32 v58, 0x3f317217, v55
	v_fmac_f32_e32 v52, v26, v46
	v_sub_f32_e32 v56, v56, v58
	v_fmac_f32_e32 v52, v27, v47
	v_mul_f32_e32 v67, 0x3d800000, v56
	v_fmac_f32_e32 v52, v28, v48
	v_add_f32_e32 v54, v54, v67
	v_fmac_f32_e32 v52, v29, v49
	v_fmac_f32_e32 v52, v30, v50
	v_fmac_f32_e32 v52, v31, v51
	ds_read_b128 v[36:39], v2 offset:384
	ds_read_b128 v[40:43], v2 offset:400
	ds_read_b128 v[44:47], v2 offset:416
	ds_read_b128 v[48:51], v2 offset:432
	s_waitcnt lgkmcnt(4)
; DI float logsig16(float z) { return (fminf(z, 0.f) - __logf(1.f + __expf(-fabsf(z)))) * (1.f / 16.f); }
; DI void phase_gla_prep(const Params& p, int g, char* smem, int bid, int nb) {
;     ...
;     float tsum = 0.f;
;     for (int tt = 0; tt < 32; ++tt) {
;       const float* l = lrs + (half * 32 + tt) * 16; float z = bg;
; #pragma unroll
;       for (int r = 0; r < 16; ++r) z += l[r] * wg[r];
;       tsum += logsig16(z);
;     }
;     tot[half * 128 + d] = tsum;
	v_fma_f32 v53, v16, v176, v32
	v_mul_f32_e64 v55, |v52|, s85
	v_fmac_f32_e32 v53, v17, v177
	v_exp_f32_e32 v55, v55
	v_fmac_f32_e32 v53, v18, v178
	v_min_f32_e32 v56, 0, v52
	v_fmac_f32_e32 v53, v19, v179
	v_add_f32_e32 v55, 1.0, v55
	v_fmac_f32_e32 v53, v20, v180
	v_log_f32_e32 v55, v55
	v_fmac_f32_e32 v53, v21, v181
	v_fmac_f32_e32 v53, v22, v182
	v_mul_f32_e32 v57, 0x3f317217, v55
	v_fmac_f32_e32 v53, v23, v183
	v_fma_f32 v58, v55, s74, -v57
	v_fmac_f32_e32 v53, v24, v184
	v_fmac_f32_e32 v58, 0x3377d1cf, v55
	v_fmac_f32_e32 v53, v25, v185
	v_fmac_f32_e32 v58, 0x3f317217, v55
	v_fmac_f32_e32 v53, v26, v186
	v_sub_f32_e32 v56, v56, v58
	v_fmac_f32_e32 v53, v27, v187
	v_mul_f32_e32 v68, 0x3d800000, v56
	v_fmac_f32_e32 v53, v28, v188
	v_add_f32_e32 v54, v54, v68
	v_fmac_f32_e32 v53, v29, v189
	v_fmac_f32_e32 v53, v30, v190
	v_fmac_f32_e32 v53, v31, v191
	ds_read_b128 v[176:179], v2 offset:448
	ds_read_b128 v[180:183], v2 offset:464
	ds_read_b128 v[184:187], v2 offset:480
	ds_read_b128 v[188:191], v2 offset:496
	s_waitcnt lgkmcnt(4)
	v_fma_f32 v52, v16, v36, v32
	v_mul_f32_e64 v55, |v53|, s85
	v_fmac_f32_e32 v52, v17, v37
	v_exp_f32_e32 v55, v55
	v_fmac_f32_e32 v52, v18, v38
	v_min_f32_e32 v56, 0, v53
	v_fmac_f32_e32 v52, v19, v39
	v_add_f32_e32 v55, 1.0, v55
	v_fmac_f32_e32 v52, v20, v40
	v_log_f32_e32 v55, v55
	v_fmac_f32_e32 v52, v21, v41
	v_fmac_f32_e32 v52, v22, v42
	v_mul_f32_e32 v57, 0x3f317217, v55
	v_fmac_f32_e32 v52, v23, v43
	v_fma_f32 v58, v55, s74, -v57
	v_fmac_f32_e32 v52, v24, v44
	v_fmac_f32_e32 v58, 0x3377d1cf, v55
	v_fmac_f32_e32 v52, v25, v45
	v_fmac_f32_e32 v58, 0x3f317217, v55
	v_fmac_f32_e32 v52, v26, v46
	v_sub_f32_e32 v56, v56, v58
	v_fmac_f32_e32 v52, v27, v47
	v_mul_f32_e32 v69, 0x3d800000, v56
	v_fmac_f32_e32 v52, v28, v48
	v_add_f32_e32 v54, v54, v69
	v_fmac_f32_e32 v52, v29, v49
	v_fmac_f32_e32 v52, v30, v50
	v_fmac_f32_e32 v52, v31, v51
	ds_read_b128 v[36:39], v2 offset:512
	ds_read_b128 v[40:43], v2 offset:528
	ds_read_b128 v[44:47], v2 offset:544
	ds_read_b128 v[48:51], v2 offset:560
	s_waitcnt lgkmcnt(4)
	v_fma_f32 v53, v16, v176, v32
	v_mul_f32_e64 v55, |v52|, s85
	v_fmac_f32_e32 v53, v17, v177
	v_exp_f32_e32 v55, v55
	v_fmac_f32_e32 v53, v18, v178
	v_min_f32_e32 v56, 0, v52
	v_fmac_f32_e32 v53, v19, v179
	v_add_f32_e32 v55, 1.0, v55
	v_fmac_f32_e32 v53, v20, v180
	v_log_f32_e32 v55, v55
	v_fmac_f32_e32 v53, v21, v181
	v_fmac_f32_e32 v53, v22, v182
	v_mul_f32_e32 v57, 0x3f317217, v55
	v_fmac_f32_e32 v53, v23, v183
	v_fma_f32 v58, v55, s74, -v57
	v_fmac_f32_e32 v53, v24, v184
	v_fmac_f32_e32 v58, 0x3377d1cf, v55
	v_fmac_f32_e32 v53, v25, v185
	v_fmac_f32_e32 v58, 0x3f317217, v55
	v_fmac_f32_e32 v53, v26, v186
	v_sub_f32_e32 v56, v56, v58
	v_fmac_f32_e32 v53, v27, v187
	v_mul_f32_e32 v70, 0x3d800000, v56
	v_fmac_f32_e32 v53, v28, v188
	v_add_f32_e32 v54, v54, v70
	v_fmac_f32_e32 v53, v29, v189
	v_fmac_f32_e32 v53, v30, v190
	v_fmac_f32_e32 v53, v31, v191
	ds_read_b128 v[176:179], v2 offset:576
	ds_read_b128 v[180:183], v2 offset:592
	ds_read_b128 v[184:187], v2 offset:608
	ds_read_b128 v[188:191], v2 offset:624
	s_waitcnt lgkmcnt(4)
	v_fma_f32 v52, v16, v36, v32
	v_mul_f32_e64 v55, |v53|, s85
	v_fmac_f32_e32 v52, v17, v37
	v_exp_f32_e32 v55, v55
	v_fmac_f32_e32 v52, v18, v38
	v_min_f32_e32 v56, 0, v53
	v_fmac_f32_e32 v52, v19, v39
	v_add_f32_e32 v55, 1.0, v55
	v_fmac_f32_e32 v52, v20, v40
	v_log_f32_e32 v55, v55
	v_fmac_f32_e32 v52, v21, v41
	v_fmac_f32_e32 v52, v22, v42
	v_mul_f32_e32 v57, 0x3f317217, v55
	v_fmac_f32_e32 v52, v23, v43
	v_fma_f32 v58, v55, s74, -v57
	v_fmac_f32_e32 v52, v24, v44
	v_fmac_f32_e32 v58, 0x3377d1cf, v55
	v_fmac_f32_e32 v52, v25, v45
	v_fmac_f32_e32 v58, 0x3f317217, v55
	v_fmac_f32_e32 v52, v26, v46
	v_sub_f32_e32 v56, v56, v58
	v_fmac_f32_e32 v52, v27, v47
	v_mul_f32_e32 v71, 0x3d800000, v56
	v_fmac_f32_e32 v52, v28, v48
	v_add_f32_e32 v54, v54, v71
	v_fmac_f32_e32 v52, v29, v49
	v_fmac_f32_e32 v52, v30, v50
	v_fmac_f32_e32 v52, v31, v51
	ds_read_b128 v[36:39], v2 offset:640
	ds_read_b128 v[40:43], v2 offset:656
	ds_read_b128 v[44:47], v2 offset:672
	ds_read_b128 v[48:51], v2 offset:688
	s_waitcnt lgkmcnt(4)
	v_fma_f32 v53, v16, v176, v32
	v_mul_f32_e64 v55, |v52|, s85
	v_fmac_f32_e32 v53, v17, v177
	v_exp_f32_e32 v55, v55
	v_fmac_f32_e32 v53, v18, v178
	v_min_f32_e32 v56, 0, v52
	v_fmac_f32_e32 v53, v19, v179
	v_add_f32_e32 v55, 1.0, v55
	v_fmac_f32_e32 v53, v20, v180
	v_log_f32_e32 v55, v55
	v_fmac_f32_e32 v53, v21, v181
	v_fmac_f32_e32 v53, v22, v182
	v_mul_f32_e32 v57, 0x3f317217, v55
	v_fmac_f32_e32 v53, v23, v183
	v_fma_f32 v58, v55, s74, -v57
	v_fmac_f32_e32 v53, v24, v184
	v_fmac_f32_e32 v58, 0x3377d1cf, v55
	v_fmac_f32_e32 v53, v25, v185
	v_fmac_f32_e32 v58, 0x3f317217, v55
	v_fmac_f32_e32 v53, v26, v186
	v_sub_f32_e32 v56, v56, v58
	v_fmac_f32_e32 v53, v27, v187
	v_mul_f32_e32 v72, 0x3d800000, v56
	v_fmac_f32_e32 v53, v28, v188
	v_add_f32_e32 v54, v54, v72
	v_fmac_f32_e32 v53, v29, v189
	v_fmac_f32_e32 v53, v30, v190
	v_fmac_f32_e32 v53, v31, v191
	ds_read_b128 v[176:179], v2 offset:704
	ds_read_b128 v[180:183], v2 offset:720
	ds_read_b128 v[184:187], v2 offset:736
	ds_read_b128 v[188:191], v2 offset:752
	s_waitcnt vmcnt(24)
; DI float bf2f(bf16_t v) { return __uint_as_float(((unsigned)v) << 16); }
; DI float logsig16(float z) { return (fminf(z, 0.f) - __logf(1.f + __expf(-fabsf(z)))) * (1.f / 16.f); }
; DI void phase_gla_prep(const Params& p, int g, char* smem, int bid, int nb) {
;     ...
;     float tsum = 0.f;
;     for (int tt = 0; tt < 32; ++tt) {
;       const float* l = lrs + (half * 32 + tt) * 16; float z = bg;
; #pragma unroll
;       for (int r = 0; r < 16; ++r) z += l[r] * wg[r];
;       tsum += logsig16(z);
;     }
;     tot[half * 128 + d] = tsum;
;     ...
;       const float qv = bf2f(proj[tg * NPROJ + PQG + dd]), kv = bf2f(proj[tg * NPROJ + PKG + dd]);
	global_load_ushort v112, v4, s[22:23]
	global_load_ushort v160, v4, s[22:23] offset:1024
	s_add_u32 s22, s22, 0x2800
	s_addc_u32 s23, s23, 0
	global_load_ushort v113, v4, s[22:23]
	global_load_ushort v161, v4, s[22:23] offset:1024
	s_add_u32 s22, s22, 0x2800
	s_addc_u32 s23, s23, 0
	global_load_ushort v114, v4, s[22:23]
	global_load_ushort v162, v4, s[22:23] offset:1024
	s_add_u32 s22, s22, 0x2800
	s_addc_u32 s23, s23, 0
	global_load_ushort v115, v4, s[22:23]
	global_load_ushort v163, v4, s[22:23] offset:1024
	s_add_u32 s22, s22, 0x2800
	s_addc_u32 s23, s23, 0
	global_load_ushort v116, v4, s[22:23]
	global_load_ushort v164, v4, s[22:23] offset:1024
	s_add_u32 s22, s22, 0x2800
	s_addc_u32 s23, s23, 0
	global_load_ushort v117, v4, s[22:23]
	global_load_ushort v165, v4, s[22:23] offset:1024
	s_add_u32 s22, s22, 0x2800
	s_addc_u32 s23, s23, 0
	global_load_ushort v118, v4, s[22:23]
	global_load_ushort v166, v4, s[22:23] offset:1024
	s_add_u32 s22, s22, 0x2800
	s_addc_u32 s23, s23, 0
	global_load_ushort v119, v4, s[22:23]
	global_load_ushort v167, v4, s[22:23] offset:1024
	s_add_u32 s22, s22, 0x2800
	s_addc_u32 s23, s23, 0
	global_load_ushort v120, v4, s[22:23]
	global_load_ushort v168, v4, s[22:23] offset:1024
	s_add_u32 s22, s22, 0x2800
	s_addc_u32 s23, s23, 0
	global_load_ushort v121, v4, s[22:23]
	global_load_ushort v169, v4, s[22:23] offset:1024
	s_add_u32 s22, s22, 0x2800
	s_addc_u32 s23, s23, 0
	global_load_ushort v122, v4, s[22:23]
	global_load_ushort v170, v4, s[22:23] offset:1024
	s_add_u32 s22, s22, 0x2800
	s_addc_u32 s23, s23, 0
	global_load_ushort v123, v4, s[22:23]
	global_load_ushort v171, v4, s[22:23] offset:1024
	s_add_u32 s22, s22, 0x2800
	s_addc_u32 s23, s23, 0
	global_load_ushort v124, v4, s[22:23]
	global_load_ushort v172, v4, s[22:23] offset:1024
	s_add_u32 s22, s22, 0x2800
	s_addc_u32 s23, s23, 0
	global_load_ushort v125, v4, s[22:23]
	global_load_ushort v173, v4, s[22:23] offset:1024
	s_add_u32 s22, s22, 0x2800
	s_addc_u32 s23, s23, 0
	global_load_ushort v126, v4, s[22:23]
	global_load_ushort v174, v4, s[22:23] offset:1024
	s_add_u32 s22, s22, 0x2800
	s_addc_u32 s23, s23, 0
	global_load_ushort v127, v4, s[22:23]
	global_load_ushort v175, v4, s[22:23] offset:1024
	s_add_u32 s22, s22, 0x2800
	s_addc_u32 s23, s23, 0
	s_waitcnt lgkmcnt(4)
	v_fma_f32 v52, v16, v36, v32
	v_mul_f32_e64 v55, |v53|, s85
	v_fmac_f32_e32 v52, v17, v37
	v_exp_f32_e32 v55, v55
	v_fmac_f32_e32 v52, v18, v38
	v_min_f32_e32 v56, 0, v53
	v_fmac_f32_e32 v52, v19, v39
	v_add_f32_e32 v55, 1.0, v55
	v_fmac_f32_e32 v52, v20, v40
	v_log_f32_e32 v55, v55
	v_fmac_f32_e32 v52, v21, v41
	v_fmac_f32_e32 v52, v22, v42
	v_mul_f32_e32 v57, 0x3f317217, v55
	v_fmac_f32_e32 v52, v23, v43
	v_fma_f32 v58, v55, s74, -v57
	v_fmac_f32_e32 v52, v24, v44
	v_fmac_f32_e32 v58, 0x3377d1cf, v55
	v_fmac_f32_e32 v52, v25, v45
	v_fmac_f32_e32 v58, 0x3f317217, v55
	v_fmac_f32_e32 v52, v26, v46
	v_sub_f32_e32 v56, v56, v58
	v_fmac_f32_e32 v52, v27, v47
	v_mul_f32_e32 v73, 0x3d800000, v56
	v_fmac_f32_e32 v52, v28, v48
	v_add_f32_e32 v54, v54, v73
	v_fmac_f32_e32 v52, v29, v49
	v_fmac_f32_e32 v52, v30, v50
	v_fmac_f32_e32 v52, v31, v51
	ds_read_b128 v[36:39], v2 offset:768
	ds_read_b128 v[40:43], v2 offset:784
	ds_read_b128 v[44:47], v2 offset:800
	ds_read_b128 v[48:51], v2 offset:816
	s_waitcnt lgkmcnt(4)
	v_fma_f32 v53, v16, v176, v32
	v_mul_f32_e64 v55, |v52|, s85
	v_fmac_f32_e32 v53, v17, v177
	v_exp_f32_e32 v55, v55
	v_fmac_f32_e32 v53, v18, v178
	v_min_f32_e32 v56, 0, v52
	v_fmac_f32_e32 v53, v19, v179
	v_add_f32_e32 v55, 1.0, v55
	v_fmac_f32_e32 v53, v20, v180
	v_log_f32_e32 v55, v55
	v_fmac_f32_e32 v53, v21, v181
	v_fmac_f32_e32 v53, v22, v182
	v_mul_f32_e32 v57, 0x3f317217, v55
	v_fmac_f32_e32 v53, v23, v183
	v_fma_f32 v58, v55, s74, -v57
	v_fmac_f32_e32 v53, v24, v184
	v_fmac_f32_e32 v58, 0x3377d1cf, v55
	v_fmac_f32_e32 v53, v25, v185
	v_fmac_f32_e32 v58, 0x3f317217, v55
	v_fmac_f32_e32 v53, v26, v186
	v_sub_f32_e32 v56, v56, v58
	v_fmac_f32_e32 v53, v27, v187
	v_mul_f32_e32 v74, 0x3d800000, v56
	v_fmac_f32_e32 v53, v28, v188
	v_add_f32_e32 v54, v54, v74
	v_fmac_f32_e32 v53, v29, v189
	v_fmac_f32_e32 v53, v30, v190
	v_fmac_f32_e32 v53, v31, v191
	ds_read_b128 v[176:179], v2 offset:832
	ds_read_b128 v[180:183], v2 offset:848
	ds_read_b128 v[184:187], v2 offset:864
	ds_read_b128 v[188:191], v2 offset:880
	s_waitcnt lgkmcnt(4)
	v_fma_f32 v52, v16, v36, v32
	v_mul_f32_e64 v55, |v53|, s85
	v_fmac_f32_e32 v52, v17, v37
	v_exp_f32_e32 v55, v55
	v_fmac_f32_e32 v52, v18, v38
	v_min_f32_e32 v56, 0, v53
	v_fmac_f32_e32 v52, v19, v39
	v_add_f32_e32 v55, 1.0, v55
	v_fmac_f32_e32 v52, v20, v40
	v_log_f32_e32 v55, v55
	v_fmac_f32_e32 v52, v21, v41
	v_fmac_f32_e32 v52, v22, v42
	v_mul_f32_e32 v57, 0x3f317217, v55
	v_fmac_f32_e32 v52, v23, v43
	v_fma_f32 v58, v55, s74, -v57
	v_fmac_f32_e32 v52, v24, v44
	v_fmac_f32_e32 v58, 0x3377d1cf, v55
	v_fmac_f32_e32 v52, v25, v45
	v_fmac_f32_e32 v58, 0x3f317217, v55
	v_fmac_f32_e32 v52, v26, v46
	v_sub_f32_e32 v56, v56, v58
	v_fmac_f32_e32 v52, v27, v47
	v_mul_f32_e32 v75, 0x3d800000, v56
	v_fmac_f32_e32 v52, v28, v48
	v_add_f32_e32 v54, v54, v75
	v_fmac_f32_e32 v52, v29, v49
	v_fmac_f32_e32 v52, v30, v50
	v_fmac_f32_e32 v52, v31, v51
	ds_read_b128 v[36:39], v2 offset:896
	ds_read_b128 v[40:43], v2 offset:912
	ds_read_b128 v[44:47], v2 offset:928
	ds_read_b128 v[48:51], v2 offset:944
	s_waitcnt lgkmcnt(4)
; DI float logsig16(float z) { return (fminf(z, 0.f) - __logf(1.f + __expf(-fabsf(z)))) * (1.f / 16.f); }
; DI void phase_gla_prep(const Params& p, int g, char* smem, int bid, int nb) {
;     ...
;     float tsum = 0.f;
;     for (int tt = 0; tt < 32; ++tt) {
;       const float* l = lrs + (half * 32 + tt) * 16; float z = bg;
; #pragma unroll
;       for (int r = 0; r < 16; ++r) z += l[r] * wg[r];
;       tsum += logsig16(z);
;     }
;     tot[half * 128 + d] = tsum;
	v_fma_f32 v53, v16, v176, v32
	v_mul_f32_e64 v55, |v52|, s85
	v_fmac_f32_e32 v53, v17, v177
	v_exp_f32_e32 v55, v55
	v_fmac_f32_e32 v53, v18, v178
	v_min_f32_e32 v56, 0, v52
	v_fmac_f32_e32 v53, v19, v179
	v_add_f32_e32 v55, 1.0, v55
	v_fmac_f32_e32 v53, v20, v180
	v_log_f32_e32 v55, v55
	v_fmac_f32_e32 v53, v21, v181
	v_fmac_f32_e32 v53, v22, v182
	v_mul_f32_e32 v57, 0x3f317217, v55
	v_fmac_f32_e32 v53, v23, v183
	v_fma_f32 v58, v55, s74, -v57
	v_fmac_f32_e32 v53, v24, v184
	v_fmac_f32_e32 v58, 0x3377d1cf, v55
	v_fmac_f32_e32 v53, v25, v185
	v_fmac_f32_e32 v58, 0x3f317217, v55
	v_fmac_f32_e32 v53, v26, v186
	v_sub_f32_e32 v56, v56, v58
	v_fmac_f32_e32 v53, v27, v187
	v_mul_f32_e32 v76, 0x3d800000, v56
	v_fmac_f32_e32 v53, v28, v188
	v_add_f32_e32 v54, v54, v76
	v_fmac_f32_e32 v53, v29, v189
	v_fmac_f32_e32 v53, v30, v190
	v_fmac_f32_e32 v53, v31, v191
	ds_read_b128 v[176:179], v2 offset:960
	ds_read_b128 v[180:183], v2 offset:976
	ds_read_b128 v[184:187], v2 offset:992
	ds_read_b128 v[188:191], v2 offset:1008
	s_waitcnt lgkmcnt(4)
	v_fma_f32 v52, v16, v36, v32
	v_mul_f32_e64 v55, |v53|, s85
	v_fmac_f32_e32 v52, v17, v37
	v_exp_f32_e32 v55, v55
	v_fmac_f32_e32 v52, v18, v38
	v_min_f32_e32 v56, 0, v53
	v_fmac_f32_e32 v52, v19, v39
	v_add_f32_e32 v55, 1.0, v55
	v_fmac_f32_e32 v52, v20, v40
	v_log_f32_e32 v55, v55
	v_fmac_f32_e32 v52, v21, v41
	v_fmac_f32_e32 v52, v22, v42
	v_mul_f32_e32 v57, 0x3f317217, v55
	v_fmac_f32_e32 v52, v23, v43
	v_fma_f32 v58, v55, s74, -v57
	v_fmac_f32_e32 v52, v24, v44
	v_fmac_f32_e32 v58, 0x3377d1cf, v55
	v_fmac_f32_e32 v52, v25, v45
	v_fmac_f32_e32 v58, 0x3f317217, v55
	v_fmac_f32_e32 v52, v26, v46
	v_sub_f32_e32 v56, v56, v58
	v_fmac_f32_e32 v52, v27, v47
	v_mul_f32_e32 v77, 0x3d800000, v56
	v_fmac_f32_e32 v52, v28, v48
	v_add_f32_e32 v54, v54, v77
	v_fmac_f32_e32 v52, v29, v49
	v_fmac_f32_e32 v52, v30, v50
	v_fmac_f32_e32 v52, v31, v51
	ds_read_b128 v[36:39], v2 offset:1024
	ds_read_b128 v[40:43], v2 offset:1040
	ds_read_b128 v[44:47], v2 offset:1056
	ds_read_b128 v[48:51], v2 offset:1072
	s_waitcnt lgkmcnt(4)
	v_fma_f32 v53, v16, v176, v32
	v_mul_f32_e64 v55, |v52|, s85
	v_fmac_f32_e32 v53, v17, v177
	v_exp_f32_e32 v55, v55
	v_fmac_f32_e32 v53, v18, v178
	v_min_f32_e32 v56, 0, v52
	v_fmac_f32_e32 v53, v19, v179
	v_add_f32_e32 v55, 1.0, v55
	v_fmac_f32_e32 v53, v20, v180
	v_log_f32_e32 v55, v55
	v_fmac_f32_e32 v53, v21, v181
	v_fmac_f32_e32 v53, v22, v182
	v_mul_f32_e32 v57, 0x3f317217, v55
	v_fmac_f32_e32 v53, v23, v183
	v_fma_f32 v58, v55, s74, -v57
	v_fmac_f32_e32 v53, v24, v184
	v_fmac_f32_e32 v58, 0x3377d1cf, v55
	v_fmac_f32_e32 v53, v25, v185
	v_fmac_f32_e32 v58, 0x3f317217, v55
	v_fmac_f32_e32 v53, v26, v186
	v_sub_f32_e32 v56, v56, v58
	v_fmac_f32_e32 v53, v27, v187
	v_mul_f32_e32 v78, 0x3d800000, v56
	v_fmac_f32_e32 v53, v28, v188
	v_add_f32_e32 v54, v54, v78
	v_fmac_f32_e32 v53, v29, v189
	v_fmac_f32_e32 v53, v30, v190
	v_fmac_f32_e32 v53, v31, v191
	ds_read_b128 v[176:179], v2 offset:1088
	ds_read_b128 v[180:183], v2 offset:1104
	ds_read_b128 v[184:187], v2 offset:1120
	ds_read_b128 v[188:191], v2 offset:1136
	s_waitcnt lgkmcnt(4)
	v_fma_f32 v52, v16, v36, v32
	v_mul_f32_e64 v55, |v53|, s85
	v_fmac_f32_e32 v52, v17, v37
	v_exp_f32_e32 v55, v55
	v_fmac_f32_e32 v52, v18, v38
	v_min_f32_e32 v56, 0, v53
	v_fmac_f32_e32 v52, v19, v39
	v_add_f32_e32 v55, 1.0, v55
	v_fmac_f32_e32 v52, v20, v40
	v_log_f32_e32 v55, v55
	v_fmac_f32_e32 v52, v21, v41
	v_fmac_f32_e32 v52, v22, v42
	v_mul_f32_e32 v57, 0x3f317217, v55
	v_fmac_f32_e32 v52, v23, v43
	v_fma_f32 v58, v55, s74, -v57
	v_fmac_f32_e32 v52, v24, v44
	v_fmac_f32_e32 v58, 0x3377d1cf, v55
	v_fmac_f32_e32 v52, v25, v45
	v_fmac_f32_e32 v58, 0x3f317217, v55
	v_fmac_f32_e32 v52, v26, v46
	v_sub_f32_e32 v56, v56, v58
	v_fmac_f32_e32 v52, v27, v47
	v_mul_f32_e32 v79, 0x3d800000, v56
	v_fmac_f32_e32 v52, v28, v48
	v_add_f32_e32 v54, v54, v79
	v_fmac_f32_e32 v52, v29, v49
	v_fmac_f32_e32 v52, v30, v50
	v_fmac_f32_e32 v52, v31, v51
	ds_read_b128 v[36:39], v2 offset:1152
	ds_read_b128 v[40:43], v2 offset:1168
	ds_read_b128 v[44:47], v2 offset:1184
	ds_read_b128 v[48:51], v2 offset:1200
	s_waitcnt lgkmcnt(4)
	v_fma_f32 v53, v16, v176, v32
	v_mul_f32_e64 v55, |v52|, s85
	v_fmac_f32_e32 v53, v17, v177
	v_exp_f32_e32 v55, v55
	v_fmac_f32_e32 v53, v18, v178
	v_min_f32_e32 v56, 0, v52
	v_fmac_f32_e32 v53, v19, v179
	v_add_f32_e32 v55, 1.0, v55
	v_fmac_f32_e32 v53, v20, v180
	v_log_f32_e32 v55, v55
	v_fmac_f32_e32 v53, v21, v181
	v_fmac_f32_e32 v53, v22, v182
	v_mul_f32_e32 v57, 0x3f317217, v55
	v_fmac_f32_e32 v53, v23, v183
	v_fma_f32 v58, v55, s74, -v57
	v_fmac_f32_e32 v53, v24, v184
	v_fmac_f32_e32 v58, 0x3377d1cf, v55
	v_fmac_f32_e32 v53, v25, v185
	v_fmac_f32_e32 v58, 0x3f317217, v55
	v_fmac_f32_e32 v53, v26, v186
	v_sub_f32_e32 v56, v56, v58
	v_fmac_f32_e32 v53, v27, v187
	v_mul_f32_e32 v80, 0x3d800000, v56
	v_fmac_f32_e32 v53, v28, v188
	v_add_f32_e32 v54, v54, v80
	v_fmac_f32_e32 v53, v29, v189
	v_fmac_f32_e32 v53, v30, v190
	v_fmac_f32_e32 v53, v31, v191
	ds_read_b128 v[176:179], v2 offset:1216
	ds_read_b128 v[180:183], v2 offset:1232
	ds_read_b128 v[184:187], v2 offset:1248
	ds_read_b128 v[188:191], v2 offset:1264
	s_waitcnt lgkmcnt(4)
; DI float logsig16(float z) { return (fminf(z, 0.f) - __logf(1.f + __expf(-fabsf(z)))) * (1.f / 16.f); }
; DI void phase_gla_prep(const Params& p, int g, char* smem, int bid, int nb) {
;     ...
;     float tsum = 0.f;
;     for (int tt = 0; tt < 32; ++tt) {
;       const float* l = lrs + (half * 32 + tt) * 16; float z = bg;
; #pragma unroll
;       for (int r = 0; r < 16; ++r) z += l[r] * wg[r];
;       tsum += logsig16(z);
;     }
;     tot[half * 128 + d] = tsum;
	v_fma_f32 v52, v16, v36, v32
	v_mul_f32_e64 v55, |v53|, s85
	v_fmac_f32_e32 v52, v17, v37
	v_exp_f32_e32 v55, v55
	v_fmac_f32_e32 v52, v18, v38
	v_min_f32_e32 v56, 0, v53
	v_fmac_f32_e32 v52, v19, v39
	v_add_f32_e32 v55, 1.0, v55
	v_fmac_f32_e32 v52, v20, v40
	v_log_f32_e32 v55, v55
	v_fmac_f32_e32 v52, v21, v41
	v_fmac_f32_e32 v52, v22, v42
	v_mul_f32_e32 v57, 0x3f317217, v55
	v_fmac_f32_e32 v52, v23, v43
	v_fma_f32 v58, v55, s74, -v57
	v_fmac_f32_e32 v52, v24, v44
	v_fmac_f32_e32 v58, 0x3377d1cf, v55
	v_fmac_f32_e32 v52, v25, v45
	v_fmac_f32_e32 v58, 0x3f317217, v55
	v_fmac_f32_e32 v52, v26, v46
	v_sub_f32_e32 v56, v56, v58
	v_fmac_f32_e32 v52, v27, v47
	v_mul_f32_e32 v81, 0x3d800000, v56
	v_fmac_f32_e32 v52, v28, v48
	v_add_f32_e32 v54, v54, v81
	v_fmac_f32_e32 v52, v29, v49
	v_fmac_f32_e32 v52, v30, v50
	v_fmac_f32_e32 v52, v31, v51
	ds_read_b128 v[36:39], v2 offset:1280
	ds_read_b128 v[40:43], v2 offset:1296
	ds_read_b128 v[44:47], v2 offset:1312
	ds_read_b128 v[48:51], v2 offset:1328
	s_waitcnt lgkmcnt(4)
	v_fma_f32 v53, v16, v176, v32
	v_mul_f32_e64 v55, |v52|, s85
	v_fmac_f32_e32 v53, v17, v177
	v_exp_f32_e32 v55, v55
	v_fmac_f32_e32 v53, v18, v178
	v_min_f32_e32 v56, 0, v52
	v_fmac_f32_e32 v53, v19, v179
	v_add_f32_e32 v55, 1.0, v55
	v_fmac_f32_e32 v53, v20, v180
	v_log_f32_e32 v55, v55
	v_fmac_f32_e32 v53, v21, v181
	v_fmac_f32_e32 v53, v22, v182
	v_mul_f32_e32 v57, 0x3f317217, v55
	v_fmac_f32_e32 v53, v23, v183
	v_fma_f32 v58, v55, s74, -v57
	v_fmac_f32_e32 v53, v24, v184
	v_fmac_f32_e32 v58, 0x3377d1cf, v55
	v_fmac_f32_e32 v53, v25, v185
	v_fmac_f32_e32 v58, 0x3f317217, v55
	v_fmac_f32_e32 v53, v26, v186
	v_sub_f32_e32 v56, v56, v58
	v_fmac_f32_e32 v53, v27, v187
	v_mul_f32_e32 v82, 0x3d800000, v56
	v_fmac_f32_e32 v53, v28, v188
	v_add_f32_e32 v54, v54, v82
	v_fmac_f32_e32 v53, v29, v189
	v_fmac_f32_e32 v53, v30, v190
	v_fmac_f32_e32 v53, v31, v191
	ds_read_b128 v[176:179], v2 offset:1344
	ds_read_b128 v[180:183], v2 offset:1360
	ds_read_b128 v[184:187], v2 offset:1376
	ds_read_b128 v[188:191], v2 offset:1392
	s_waitcnt lgkmcnt(4)
	v_fma_f32 v52, v16, v36, v32
	v_mul_f32_e64 v55, |v53|, s85
	v_fmac_f32_e32 v52, v17, v37
	v_exp_f32_e32 v55, v55
	v_fmac_f32_e32 v52, v18, v38
	v_min_f32_e32 v56, 0, v53
	v_fmac_f32_e32 v52, v19, v39
	v_add_f32_e32 v55, 1.0, v55
	v_fmac_f32_e32 v52, v20, v40
	v_log_f32_e32 v55, v55
	v_fmac_f32_e32 v52, v21, v41
	v_fmac_f32_e32 v52, v22, v42
	v_mul_f32_e32 v57, 0x3f317217, v55
	v_fmac_f32_e32 v52, v23, v43
	v_fma_f32 v58, v55, s74, -v57
	v_fmac_f32_e32 v52, v24, v44
	v_fmac_f32_e32 v58, 0x3377d1cf, v55
	v_fmac_f32_e32 v52, v25, v45
	v_fmac_f32_e32 v58, 0x3f317217, v55
	v_fmac_f32_e32 v52, v26, v46
	v_sub_f32_e32 v56, v56, v58
	v_fmac_f32_e32 v52, v27, v47
	v_mul_f32_e32 v83, 0x3d800000, v56
	v_fmac_f32_e32 v52, v28, v48
	v_add_f32_e32 v54, v54, v83
	v_fmac_f32_e32 v52, v29, v49
	v_fmac_f32_e32 v52, v30, v50
	v_fmac_f32_e32 v52, v31, v51
	ds_read_b128 v[36:39], v2 offset:1408
	ds_read_b128 v[40:43], v2 offset:1424
	ds_read_b128 v[44:47], v2 offset:1440
	ds_read_b128 v[48:51], v2 offset:1456
	s_waitcnt lgkmcnt(4)
	v_fma_f32 v53, v16, v176, v32
	v_mul_f32_e64 v55, |v52|, s85
	v_fmac_f32_e32 v53, v17, v177
	v_exp_f32_e32 v55, v55
	v_fmac_f32_e32 v53, v18, v178
	v_min_f32_e32 v56, 0, v52
	v_fmac_f32_e32 v53, v19, v179
	v_add_f32_e32 v55, 1.0, v55
	v_fmac_f32_e32 v53, v20, v180
	v_log_f32_e32 v55, v55
	v_fmac_f32_e32 v53, v21, v181
	v_fmac_f32_e32 v53, v22, v182
	v_mul_f32_e32 v57, 0x3f317217, v55
	v_fmac_f32_e32 v53, v23, v183
	v_fma_f32 v58, v55, s74, -v57
	v_fmac_f32_e32 v53, v24, v184
	v_fmac_f32_e32 v58, 0x3377d1cf, v55
	v_fmac_f32_e32 v53, v25, v185
	v_fmac_f32_e32 v58, 0x3f317217, v55
	v_fmac_f32_e32 v53, v26, v186
	v_sub_f32_e32 v56, v56, v58
	v_fmac_f32_e32 v53, v27, v187
	v_mul_f32_e32 v84, 0x3d800000, v56
	v_fmac_f32_e32 v53, v28, v188
	v_add_f32_e32 v54, v54, v84
	v_fmac_f32_e32 v53, v29, v189
	v_fmac_f32_e32 v53, v30, v190
	v_fmac_f32_e32 v53, v31, v191
	ds_read_b128 v[176:179], v2 offset:1472
	ds_read_b128 v[180:183], v2 offset:1488
	ds_read_b128 v[184:187], v2 offset:1504
	ds_read_b128 v[188:191], v2 offset:1520
	s_waitcnt lgkmcnt(4)
	v_fma_f32 v52, v16, v36, v32
	v_mul_f32_e64 v55, |v53|, s85
	v_fmac_f32_e32 v52, v17, v37
	v_exp_f32_e32 v55, v55
	v_fmac_f32_e32 v52, v18, v38
	v_min_f32_e32 v56, 0, v53
	v_fmac_f32_e32 v52, v19, v39
	v_add_f32_e32 v55, 1.0, v55
	v_fmac_f32_e32 v52, v20, v40
	v_log_f32_e32 v55, v55
	v_fmac_f32_e32 v52, v21, v41
	v_fmac_f32_e32 v52, v22, v42
	v_mul_f32_e32 v57, 0x3f317217, v55
	v_fmac_f32_e32 v52, v23, v43
	v_fma_f32 v58, v55, s74, -v57
	v_fmac_f32_e32 v52, v24, v44
	v_fmac_f32_e32 v58, 0x3377d1cf, v55
	v_fmac_f32_e32 v52, v25, v45
	v_fmac_f32_e32 v58, 0x3f317217, v55
	v_fmac_f32_e32 v52, v26, v46
	v_sub_f32_e32 v56, v56, v58
	v_fmac_f32_e32 v52, v27, v47
	v_mul_f32_e32 v85, 0x3d800000, v56
	v_fmac_f32_e32 v52, v28, v48
	v_add_f32_e32 v54, v54, v85
	v_fmac_f32_e32 v52, v29, v49
	v_fmac_f32_e32 v52, v30, v50
	v_fmac_f32_e32 v52, v31, v51
	ds_read_b128 v[36:39], v2 offset:1536
	ds_read_b128 v[40:43], v2 offset:1552
	ds_read_b128 v[44:47], v2 offset:1568
	ds_read_b128 v[48:51], v2 offset:1584
	s_waitcnt lgkmcnt(4)
; DI float logsig16(float z) { return (fminf(z, 0.f) - __logf(1.f + __expf(-fabsf(z)))) * (1.f / 16.f); }
; DI void phase_gla_prep(const Params& p, int g, char* smem, int bid, int nb) {
;     ...
;     float tsum = 0.f;
;     for (int tt = 0; tt < 32; ++tt) {
;       const float* l = lrs + (half * 32 + tt) * 16; float z = bg;
; #pragma unroll
;       for (int r = 0; r < 16; ++r) z += l[r] * wg[r];
;       tsum += logsig16(z);
;     }
;     tot[half * 128 + d] = tsum;
	v_fma_f32 v53, v16, v176, v32
	v_mul_f32_e64 v55, |v52|, s85
	v_fmac_f32_e32 v53, v17, v177
	v_exp_f32_e32 v55, v55
	v_fmac_f32_e32 v53, v18, v178
	v_min_f32_e32 v56, 0, v52
	v_fmac_f32_e32 v53, v19, v179
	v_add_f32_e32 v55, 1.0, v55
	v_fmac_f32_e32 v53, v20, v180
	v_log_f32_e32 v55, v55
	v_fmac_f32_e32 v53, v21, v181
	v_fmac_f32_e32 v53, v22, v182
	v_mul_f32_e32 v57, 0x3f317217, v55
	v_fmac_f32_e32 v53, v23, v183
	v_fma_f32 v58, v55, s74, -v57
	v_fmac_f32_e32 v53, v24, v184
	v_fmac_f32_e32 v58, 0x3377d1cf, v55
	v_fmac_f32_e32 v53, v25, v185
	v_fmac_f32_e32 v58, 0x3f317217, v55
	v_fmac_f32_e32 v53, v26, v186
	v_sub_f32_e32 v56, v56, v58
	v_fmac_f32_e32 v53, v27, v187
	v_mul_f32_e32 v86, 0x3d800000, v56
	v_fmac_f32_e32 v53, v28, v188
	v_add_f32_e32 v54, v54, v86
	v_fmac_f32_e32 v53, v29, v189
	v_fmac_f32_e32 v53, v30, v190
	v_fmac_f32_e32 v53, v31, v191
	ds_read_b128 v[176:179], v2 offset:1600
	ds_read_b128 v[180:183], v2 offset:1616
	ds_read_b128 v[184:187], v2 offset:1632
	ds_read_b128 v[188:191], v2 offset:1648
	s_waitcnt lgkmcnt(4)
	v_fma_f32 v52, v16, v36, v32
	v_mul_f32_e64 v55, |v53|, s85
	v_fmac_f32_e32 v52, v17, v37
	v_exp_f32_e32 v55, v55
	v_fmac_f32_e32 v52, v18, v38
	v_min_f32_e32 v56, 0, v53
	v_fmac_f32_e32 v52, v19, v39
	v_add_f32_e32 v55, 1.0, v55
	v_fmac_f32_e32 v52, v20, v40
	v_log_f32_e32 v55, v55
	v_fmac_f32_e32 v52, v21, v41
	v_fmac_f32_e32 v52, v22, v42
	v_mul_f32_e32 v57, 0x3f317217, v55
	v_fmac_f32_e32 v52, v23, v43
	v_fma_f32 v58, v55, s74, -v57
	v_fmac_f32_e32 v52, v24, v44
	v_fmac_f32_e32 v58, 0x3377d1cf, v55
	v_fmac_f32_e32 v52, v25, v45
	v_fmac_f32_e32 v58, 0x3f317217, v55
	v_fmac_f32_e32 v52, v26, v46
	v_sub_f32_e32 v56, v56, v58
	v_fmac_f32_e32 v52, v27, v47
	v_mul_f32_e32 v87, 0x3d800000, v56
	v_fmac_f32_e32 v52, v28, v48
	v_add_f32_e32 v54, v54, v87
	v_fmac_f32_e32 v52, v29, v49
	v_fmac_f32_e32 v52, v30, v50
	v_fmac_f32_e32 v52, v31, v51
	ds_read_b128 v[36:39], v2 offset:1664
	ds_read_b128 v[40:43], v2 offset:1680
	ds_read_b128 v[44:47], v2 offset:1696
	ds_read_b128 v[48:51], v2 offset:1712
	s_waitcnt lgkmcnt(4)
	v_fma_f32 v53, v16, v176, v32
	v_mul_f32_e64 v55, |v52|, s85
	v_fmac_f32_e32 v53, v17, v177
	v_exp_f32_e32 v55, v55
	v_fmac_f32_e32 v53, v18, v178
	v_min_f32_e32 v56, 0, v52
	v_fmac_f32_e32 v53, v19, v179
	v_add_f32_e32 v55, 1.0, v55
	v_fmac_f32_e32 v53, v20, v180
	v_log_f32_e32 v55, v55
	v_fmac_f32_e32 v53, v21, v181
	v_fmac_f32_e32 v53, v22, v182
	v_mul_f32_e32 v57, 0x3f317217, v55
	v_fmac_f32_e32 v53, v23, v183
	v_fma_f32 v58, v55, s74, -v57
	v_fmac_f32_e32 v53, v24, v184
	v_fmac_f32_e32 v58, 0x3377d1cf, v55
	v_fmac_f32_e32 v53, v25, v185
	v_fmac_f32_e32 v58, 0x3f317217, v55
	v_fmac_f32_e32 v53, v26, v186
	v_sub_f32_e32 v56, v56, v58
	v_fmac_f32_e32 v53, v27, v187
	v_mul_f32_e32 v88, 0x3d800000, v56
	v_fmac_f32_e32 v53, v28, v188
	v_add_f32_e32 v54, v54, v88
	v_fmac_f32_e32 v53, v29, v189
	v_fmac_f32_e32 v53, v30, v190
	v_fmac_f32_e32 v53, v31, v191
	ds_read_b128 v[176:179], v2 offset:1728
	ds_read_b128 v[180:183], v2 offset:1744
	ds_read_b128 v[184:187], v2 offset:1760
	ds_read_b128 v[188:191], v2 offset:1776
	s_waitcnt lgkmcnt(4)
	v_fma_f32 v52, v16, v36, v32
	v_mul_f32_e64 v55, |v53|, s85
	v_fmac_f32_e32 v52, v17, v37
	v_exp_f32_e32 v55, v55
	v_fmac_f32_e32 v52, v18, v38
	v_min_f32_e32 v56, 0, v53
	v_fmac_f32_e32 v52, v19, v39
	v_add_f32_e32 v55, 1.0, v55
	v_fmac_f32_e32 v52, v20, v40
	v_log_f32_e32 v55, v55
	v_fmac_f32_e32 v52, v21, v41
	v_fmac_f32_e32 v52, v22, v42
	v_mul_f32_e32 v57, 0x3f317217, v55
	v_fmac_f32_e32 v52, v23, v43
	v_fma_f32 v58, v55, s74, -v57
	v_fmac_f32_e32 v52, v24, v44
	v_fmac_f32_e32 v58, 0x3377d1cf, v55
	v_fmac_f32_e32 v52, v25, v45
	v_fmac_f32_e32 v58, 0x3f317217, v55
	v_fmac_f32_e32 v52, v26, v46
	v_sub_f32_e32 v56, v56, v58
	v_fmac_f32_e32 v52, v27, v47
	v_mul_f32_e32 v89, 0x3d800000, v56
	v_fmac_f32_e32 v52, v28, v48
	v_add_f32_e32 v54, v54, v89
	v_fmac_f32_e32 v52, v29, v49
	v_fmac_f32_e32 v52, v30, v50
	v_fmac_f32_e32 v52, v31, v51
	ds_read_b128 v[36:39], v2 offset:1792
	ds_read_b128 v[40:43], v2 offset:1808
	ds_read_b128 v[44:47], v2 offset:1824
	ds_read_b128 v[48:51], v2 offset:1840
	s_waitcnt lgkmcnt(4)
	v_fma_f32 v53, v16, v176, v32
	v_mul_f32_e64 v55, |v52|, s85
	v_fmac_f32_e32 v53, v17, v177
	v_exp_f32_e32 v55, v55
	v_fmac_f32_e32 v53, v18, v178
	v_min_f32_e32 v56, 0, v52
	v_fmac_f32_e32 v53, v19, v179
	v_add_f32_e32 v55, 1.0, v55
	v_fmac_f32_e32 v53, v20, v180
	v_log_f32_e32 v55, v55
	v_fmac_f32_e32 v53, v21, v181
	v_fmac_f32_e32 v53, v22, v182
	v_mul_f32_e32 v57, 0x3f317217, v55
	v_fmac_f32_e32 v53, v23, v183
	v_fma_f32 v58, v55, s74, -v57
	v_fmac_f32_e32 v53, v24, v184
	v_fmac_f32_e32 v58, 0x3377d1cf, v55
	v_fmac_f32_e32 v53, v25, v185
	v_fmac_f32_e32 v58, 0x3f317217, v55
	v_fmac_f32_e32 v53, v26, v186
	v_sub_f32_e32 v56, v56, v58
	v_fmac_f32_e32 v53, v27, v187
	v_mul_f32_e32 v90, 0x3d800000, v56
	v_fmac_f32_e32 v53, v28, v188
	v_add_f32_e32 v54, v54, v90
	v_fmac_f32_e32 v53, v29, v189
	v_fmac_f32_e32 v53, v30, v190
	v_fmac_f32_e32 v53, v31, v191
	ds_read_b128 v[176:179], v2 offset:1856
	ds_read_b128 v[180:183], v2 offset:1872
	ds_read_b128 v[184:187], v2 offset:1888
	ds_read_b128 v[188:191], v2 offset:1904
	s_waitcnt lgkmcnt(4)
; DI float logsig16(float z) { return (fminf(z, 0.f) - __logf(1.f + __expf(-fabsf(z)))) * (1.f / 16.f); }
; DI void phase_gla_prep(const Params& p, int g, char* smem, int bid, int nb) {
;     ...
;     for (int tt = 0; tt < 32; ++tt) {
;       const float* l = lrs + (half * 32 + tt) * 16; float z = bg;
; #pragma unroll
;       for (int r = 0; r < 16; ++r) z += l[r] * wg[r];
;       tsum += logsig16(z);
;     }
;     tot[half * 128 + d] = tsum;
;     __syncthreads();
	v_fma_f32 v52, v16, v36, v32
	v_mul_f32_e64 v55, |v53|, s85
	v_fmac_f32_e32 v52, v17, v37
	v_exp_f32_e32 v55, v55
	v_fmac_f32_e32 v52, v18, v38
	v_min_f32_e32 v56, 0, v53
	v_fmac_f32_e32 v52, v19, v39
	v_add_f32_e32 v55, 1.0, v55
	v_fmac_f32_e32 v52, v20, v40
	v_log_f32_e32 v55, v55
	v_fmac_f32_e32 v52, v21, v41
	v_fmac_f32_e32 v52, v22, v42
	v_mul_f32_e32 v57, 0x3f317217, v55
	v_fmac_f32_e32 v52, v23, v43
	v_fma_f32 v58, v55, s74, -v57
	v_fmac_f32_e32 v52, v24, v44
	v_fmac_f32_e32 v58, 0x3377d1cf, v55
	v_fmac_f32_e32 v52, v25, v45
	v_fmac_f32_e32 v58, 0x3f317217, v55
	v_fmac_f32_e32 v52, v26, v46
	v_sub_f32_e32 v56, v56, v58
	v_fmac_f32_e32 v52, v27, v47
	v_mul_f32_e32 v91, 0x3d800000, v56
	v_fmac_f32_e32 v52, v28, v48
	v_add_f32_e32 v54, v54, v91
	v_fmac_f32_e32 v52, v29, v49
	v_fmac_f32_e32 v52, v30, v50
	v_fmac_f32_e32 v52, v31, v51
	ds_read_b128 v[36:39], v2 offset:1920
	ds_read_b128 v[40:43], v2 offset:1936
	ds_read_b128 v[44:47], v2 offset:1952
	ds_read_b128 v[48:51], v2 offset:1968
	s_waitcnt lgkmcnt(4)
	v_fma_f32 v53, v16, v176, v32
	v_mul_f32_e64 v55, |v52|, s85
	v_fmac_f32_e32 v53, v17, v177
	v_exp_f32_e32 v55, v55
	v_fmac_f32_e32 v53, v18, v178
	v_min_f32_e32 v56, 0, v52
	v_fmac_f32_e32 v53, v19, v179
	v_add_f32_e32 v55, 1.0, v55
	v_fmac_f32_e32 v53, v20, v180
	v_log_f32_e32 v55, v55
	v_fmac_f32_e32 v53, v21, v181
	v_fmac_f32_e32 v53, v22, v182
	v_mul_f32_e32 v57, 0x3f317217, v55
	v_fmac_f32_e32 v53, v23, v183
	v_fma_f32 v58, v55, s74, -v57
	v_fmac_f32_e32 v53, v24, v184
	v_fmac_f32_e32 v58, 0x3377d1cf, v55
	v_fmac_f32_e32 v53, v25, v185
	v_fmac_f32_e32 v58, 0x3f317217, v55
	v_fmac_f32_e32 v53, v26, v186
	v_sub_f32_e32 v56, v56, v58
	v_fmac_f32_e32 v53, v27, v187
	v_mul_f32_e32 v92, 0x3d800000, v56
	v_fmac_f32_e32 v53, v28, v188
	v_add_f32_e32 v54, v54, v92
	v_fmac_f32_e32 v53, v29, v189
	v_fmac_f32_e32 v53, v30, v190
	v_fmac_f32_e32 v53, v31, v191
	ds_read_b128 v[176:179], v2 offset:1984
	ds_read_b128 v[180:183], v2 offset:2000
	ds_read_b128 v[184:187], v2 offset:2016
	ds_read_b128 v[188:191], v2 offset:2032
	s_waitcnt lgkmcnt(4)
	v_fma_f32 v52, v16, v36, v32
	v_mul_f32_e64 v55, |v53|, s85
	v_fmac_f32_e32 v52, v17, v37
	v_exp_f32_e32 v55, v55
	v_fmac_f32_e32 v52, v18, v38
	v_min_f32_e32 v56, 0, v53
	v_fmac_f32_e32 v52, v19, v39
	v_add_f32_e32 v55, 1.0, v55
	v_fmac_f32_e32 v52, v20, v40
	v_log_f32_e32 v55, v55
	v_fmac_f32_e32 v52, v21, v41
	v_fmac_f32_e32 v52, v22, v42
	v_mul_f32_e32 v57, 0x3f317217, v55
	v_fmac_f32_e32 v52, v23, v43
	v_fma_f32 v58, v55, s74, -v57
	v_fmac_f32_e32 v52, v24, v44
	v_fmac_f32_e32 v58, 0x3377d1cf, v55
	v_fmac_f32_e32 v52, v25, v45
	v_fmac_f32_e32 v58, 0x3f317217, v55
	v_fmac_f32_e32 v52, v26, v46
	v_sub_f32_e32 v56, v56, v58
	v_fmac_f32_e32 v52, v27, v47
	v_mul_f32_e32 v93, 0x3d800000, v56
	v_fmac_f32_e32 v52, v28, v48
	v_add_f32_e32 v54, v54, v93
	v_fmac_f32_e32 v52, v29, v49
	v_fmac_f32_e32 v52, v30, v50
	v_fmac_f32_e32 v52, v31, v51
	s_waitcnt lgkmcnt(0)
	v_fma_f32 v53, v16, v176, v32
	v_mul_f32_e64 v55, |v52|, s85
	v_fmac_f32_e32 v53, v17, v177
	v_exp_f32_e32 v55, v55
	v_fmac_f32_e32 v53, v18, v178
	v_min_f32_e32 v56, 0, v52
	v_fmac_f32_e32 v53, v19, v179
	v_add_f32_e32 v55, 1.0, v55
	v_fmac_f32_e32 v53, v20, v180
	v_log_f32_e32 v55, v55
	v_fmac_f32_e32 v53, v21, v181
	v_fmac_f32_e32 v53, v22, v182
	v_mul_f32_e32 v57, 0x3f317217, v55
	v_fmac_f32_e32 v53, v23, v183
	v_fma_f32 v58, v55, s74, -v57
	v_fmac_f32_e32 v53, v24, v184
	v_fmac_f32_e32 v58, 0x3377d1cf, v55
	v_fmac_f32_e32 v53, v25, v185
	v_fmac_f32_e32 v58, 0x3f317217, v55
	v_fmac_f32_e32 v53, v26, v186
	v_sub_f32_e32 v56, v56, v58
	v_fmac_f32_e32 v53, v27, v187
	v_mul_f32_e32 v94, 0x3d800000, v56
	v_fmac_f32_e32 v53, v28, v188
	v_add_f32_e32 v54, v54, v94
	v_fmac_f32_e32 v53, v29, v189
	v_fmac_f32_e32 v53, v30, v190
	v_fmac_f32_e32 v53, v31, v191
	v_mul_f32_e64 v55, |v53|, s85
	v_exp_f32_e32 v55, v55
	v_min_f32_e32 v56, 0, v53
	v_add_f32_e32 v55, 1.0, v55
	v_log_f32_e32 v55, v55
	s_nop 0
	v_mul_f32_e32 v57, 0x3f317217, v55
	v_fma_f32 v58, v55, s74, -v57
	v_fmac_f32_e32 v58, 0x3377d1cf, v55
	v_fmac_f32_e32 v58, 0x3f317217, v55
	v_sub_f32_e32 v56, v56, v58
	v_mul_f32_e32 v95, 0x3d800000, v56
	v_add_f32_e32 v54, v54, v95
	ds_write_b32 v1, v54 offset:4096
	s_waitcnt lgkmcnt(0)
	s_barrier
; DI float bf2f(bf16_t v) { return __uint_as_float(((unsigned)v) << 16); }
; DI bf16_t f2bf(float x) { return (bf16_t)(pk_bf16(x, 0.f) & 0xffffu); }
; DI float logsig16(float z) { return (fminf(z, 0.f) - __logf(1.f + __expf(-fabsf(z)))) * (1.f / 16.f); }
; DI void phase_gla_prep(const Params& p, int g, char* smem, int bid, int nb) {
;     ...
;     __syncthreads();
;     const float t0 = tot[d], t1 = tot[128 + d], TOTAL = t0 + t1;
;     float run = half ? t0 : 0.f;
;     const size_t blk = (size_t)((dir * 4 + head) * 256 + c);
;     unsigned ktp[16];
; #pragma unroll
;     for (int tt = 0; tt < 32; ++tt) {
;       const int t = half * 32 + tt;
;       const float* l = lrs + t * 16; float z = bg;
; #pragma unroll
;       for (int r = 0; r < 16; ++r) z += l[r] * wg[r];
;       const float gv = logsig16(z);
;       const float b = dir ? (TOTAL - run) : (run + gv);
;       run += gv;
;       const size_t tg = (size_t)c * 64 + t;
;       const float qv = bf2f(proj[tg * NPROJ + PQG + dd]), kv = bf2f(proj[tg * NPROJ + PKG + dd]);
;       const float qt = qv * __expf(b) * 0.08838834764831845f, kt = kv * __expf(-b);
;       gq[(blk * 64 + t) * 128 + d] = f2bf(qt);
;       const bf16_t kb = f2bf(kt);
;       gk[(blk * 64 + t) * 128 + d] = kb;
;       if (tt & 1) ktp[tt >> 1] |= ((unsigned)kb) << 16; else ktp[tt >> 1] = kb;
;     }
	ds_read_b32 v59, v3 offset:4096
	ds_read_b32 v60, v3 offset:4608
	s_cmp_lg_u32 s8, 0
	s_cselect_b64 s[0:1], -1, 0
	s_waitcnt lgkmcnt(0)
	v_add_f32_e32 v61, v59, v60
	v_cndmask_b32_e64 v62, 0, v59, s[0:1]
	s_waitcnt vmcnt(0)
	v_add_f32_e32 v63, v62, v64
	v_sub_f32_e32 v34, v61, v62
	v_add_f32_e32 v33, v63, v65
	v_sub_f32_e32 v35, v61, v63
	v_cndmask_b32_e64 v34, v34, v63, s[6:7]
	v_cndmask_b32_e64 v35, v35, v33, s[6:7]
	v_mul_f32_e32 v176, 0x3fb8aa3b, v34
	v_mul_f32_e32 v177, 0xbfb8aa3b, v34
	v_mul_f32_e32 v178, 0x3fb8aa3b, v35
	v_mul_f32_e32 v179, 0xbfb8aa3b, v35
	v_exp_f32_e32 v176, v176
	v_exp_f32_e32 v177, v177
	v_exp_f32_e32 v178, v178
	v_exp_f32_e32 v179, v179
	v_lshlrev_b32_e32 v180, 16, v96
	v_lshlrev_b32_e32 v181, 16, v144
	v_lshlrev_b32_e32 v182, 16, v97
	v_lshlrev_b32_e32 v183, 16, v145
	v_mul_f32_e32 v176, v176, v180
	v_mul_f32_e32 v177, v177, v181
	v_mul_f32_e32 v178, v178, v182
	v_mul_f32_e32 v179, v179, v183
	v_mul_f32_e32 v176, 0x3db504f3, v176
	v_mul_f32_e32 v178, 0x3db504f3, v178
	v_cvt_pk_bf16_f32 v180, v176, v178
	v_cvt_pk_bf16_f32 v128, v177, v179
	v_lshrrev_b32_e32 v182, 16, v180
	v_lshrrev_b32_e32 v183, 16, v128
	global_store_short v5, v180, s[24:25]
	global_store_short v5, v128, s[26:27]
	global_store_short v5, v182, s[24:25] offset:16
	global_store_short v5, v183, s[26:27] offset:16
	s_waitcnt vmcnt(56)
	v_add_f32_e32 v63, v33, v66
	v_sub_f32_e32 v37, v61, v33
	v_add_f32_e32 v36, v63, v67
	v_sub_f32_e32 v38, v61, v63
	v_cndmask_b32_e64 v37, v37, v63, s[6:7]
	v_cndmask_b32_e64 v38, v38, v36, s[6:7]
	v_mul_f32_e32 v184, 0x3fb8aa3b, v37
	v_mul_f32_e32 v185, 0xbfb8aa3b, v37
	v_mul_f32_e32 v186, 0x3fb8aa3b, v38
	v_mul_f32_e32 v187, 0xbfb8aa3b, v38
	v_exp_f32_e32 v184, v184
	v_exp_f32_e32 v185, v185
	v_exp_f32_e32 v186, v186
	v_exp_f32_e32 v187, v187
	v_lshlrev_b32_e32 v188, 16, v98
	v_lshlrev_b32_e32 v189, 16, v146
	v_lshlrev_b32_e32 v190, 16, v99
	v_lshlrev_b32_e32 v191, 16, v147
	v_mul_f32_e32 v184, v184, v188
	v_mul_f32_e32 v185, v185, v189
	v_mul_f32_e32 v186, v186, v190
	v_mul_f32_e32 v187, v187, v191
	v_mul_f32_e32 v184, 0x3db504f3, v184
	v_mul_f32_e32 v186, 0x3db504f3, v186
	v_cvt_pk_bf16_f32 v188, v184, v186
	v_cvt_pk_bf16_f32 v129, v185, v187
	v_lshrrev_b32_e32 v190, 16, v188
	v_lshrrev_b32_e32 v191, 16, v129
	global_store_short v5, v188, s[24:25] offset:32
	global_store_short v5, v129, s[26:27] offset:32
	global_store_short v5, v190, s[24:25] offset:48
	global_store_short v5, v191, s[26:27] offset:48
	s_waitcnt vmcnt(56)
	v_add_f32_e32 v63, v36, v68
	v_sub_f32_e32 v40, v61, v36
	v_add_f32_e32 v39, v63, v69
	v_sub_f32_e32 v41, v61, v63
	v_cndmask_b32_e64 v40, v40, v63, s[6:7]
	v_cndmask_b32_e64 v41, v41, v39, s[6:7]
	v_mul_f32_e32 v42, 0x3fb8aa3b, v40
	v_mul_f32_e32 v43, 0xbfb8aa3b, v40
	v_mul_f32_e32 v44, 0x3fb8aa3b, v41
	v_mul_f32_e32 v45, 0xbfb8aa3b, v41
	v_exp_f32_e32 v42, v42
	v_exp_f32_e32 v43, v43
	v_exp_f32_e32 v44, v44
	v_exp_f32_e32 v45, v45
	v_lshlrev_b32_e32 v46, 16, v100
	v_lshlrev_b32_e32 v47, 16, v148
	v_lshlrev_b32_e32 v48, 16, v101
	v_lshlrev_b32_e32 v49, 16, v149
	v_mul_f32_e32 v42, v42, v46
	v_mul_f32_e32 v43, v43, v47
	v_mul_f32_e32 v44, v44, v48
	v_mul_f32_e32 v45, v45, v49
	v_mul_f32_e32 v42, 0x3db504f3, v42
	v_mul_f32_e32 v44, 0x3db504f3, v44
	v_cvt_pk_bf16_f32 v46, v42, v44
	v_cvt_pk_bf16_f32 v130, v43, v45
	v_lshrrev_b32_e32 v48, 16, v46
	v_lshrrev_b32_e32 v49, 16, v130
	global_store_short v5, v46, s[24:25] offset:64
	global_store_short v5, v130, s[26:27] offset:64
	global_store_short v5, v48, s[24:25] offset:80
	global_store_short v5, v49, s[26:27] offset:80
	s_waitcnt vmcnt(56)
	v_add_f32_e32 v63, v39, v70
	v_sub_f32_e32 v51, v61, v39
	v_add_f32_e32 v50, v63, v71
	v_sub_f32_e32 v52, v61, v63
	v_cndmask_b32_e64 v51, v51, v63, s[6:7]
	v_cndmask_b32_e64 v52, v52, v50, s[6:7]
	v_mul_f32_e32 v53, 0x3fb8aa3b, v51
	v_mul_f32_e32 v54, 0xbfb8aa3b, v51
	v_mul_f32_e32 v55, 0x3fb8aa3b, v52
	v_mul_f32_e32 v56, 0xbfb8aa3b, v52
	v_exp_f32_e32 v53, v53
	v_exp_f32_e32 v54, v54
	v_exp_f32_e32 v55, v55
	v_exp_f32_e32 v56, v56
	v_lshlrev_b32_e32 v57, 16, v102
	v_lshlrev_b32_e32 v58, 16, v150
	v_lshlrev_b32_e32 v59, 16, v103
	v_lshlrev_b32_e32 v60, 16, v151
	v_mul_f32_e32 v53, v53, v57
	v_mul_f32_e32 v54, v54, v58
	v_mul_f32_e32 v55, v55, v59
	v_mul_f32_e32 v56, v56, v60
	v_mul_f32_e32 v53, 0x3db504f3, v53
	v_mul_f32_e32 v55, 0x3db504f3, v55
	v_cvt_pk_bf16_f32 v57, v53, v55
	v_cvt_pk_bf16_f32 v131, v54, v56
	v_lshrrev_b32_e32 v59, 16, v57
	v_lshrrev_b32_e32 v60, 16, v131
	global_store_short v5, v57, s[24:25] offset:96
	global_store_short v5, v131, s[26:27] offset:96
	global_store_short v5, v59, s[24:25] offset:112
	global_store_short v5, v60, s[26:27] offset:112
	s_waitcnt vmcnt(56)
	v_add_f32_e32 v63, v50, v72
	v_sub_f32_e32 v34, v61, v50
	v_add_f32_e32 v33, v63, v73
	v_sub_f32_e32 v35, v61, v63
	v_cndmask_b32_e64 v34, v34, v63, s[6:7]
	v_cndmask_b32_e64 v35, v35, v33, s[6:7]
	v_mul_f32_e32 v176, 0x3fb8aa3b, v34
	v_mul_f32_e32 v177, 0xbfb8aa3b, v34
	v_mul_f32_e32 v178, 0x3fb8aa3b, v35
	v_mul_f32_e32 v179, 0xbfb8aa3b, v35
	v_exp_f32_e32 v176, v176
	v_exp_f32_e32 v177, v177
	v_exp_f32_e32 v178, v178
	v_exp_f32_e32 v179, v179
	v_lshlrev_b32_e32 v180, 16, v104
	v_lshlrev_b32_e32 v181, 16, v152
	v_lshlrev_b32_e32 v182, 16, v105
	v_lshlrev_b32_e32 v183, 16, v153
	v_mul_f32_e32 v176, v176, v180
	v_mul_f32_e32 v177, v177, v181
	v_mul_f32_e32 v178, v178, v182
	v_mul_f32_e32 v179, v179, v183
	v_mul_f32_e32 v176, 0x3db504f3, v176
	v_mul_f32_e32 v178, 0x3db504f3, v178
	v_cvt_pk_bf16_f32 v180, v176, v178
	v_cvt_pk_bf16_f32 v132, v177, v179
	v_lshrrev_b32_e32 v182, 16, v180
	v_lshrrev_b32_e32 v183, 16, v132
	global_store_short v5, v180, s[24:25] offset:128
	global_store_short v5, v132, s[26:27] offset:128
	global_store_short v5, v182, s[24:25] offset:144
	global_store_short v5, v183, s[26:27] offset:144
	s_waitcnt vmcnt(56)
; DI float bf2f(bf16_t v) { return __uint_as_float(((unsigned)v) << 16); }
; DI bf16_t f2bf(float x) { return (bf16_t)(pk_bf16(x, 0.f) & 0xffffu); }
; DI float logsig16(float z) { return (fminf(z, 0.f) - __logf(1.f + __expf(-fabsf(z)))) * (1.f / 16.f); }
; DI void phase_gla_prep(const Params& p, int g, char* smem, int bid, int nb) {
;     ...
;     for (int tt = 0; tt < 32; ++tt) {
;       const int t = half * 32 + tt;
;       const float* l = lrs + t * 16; float z = bg;
; #pragma unroll
;       for (int r = 0; r < 16; ++r) z += l[r] * wg[r];
;       const float gv = logsig16(z);
;       const float b = dir ? (TOTAL - run) : (run + gv);
;       run += gv;
;       const size_t tg = (size_t)c * 64 + t;
;       const float qv = bf2f(proj[tg * NPROJ + PQG + dd]), kv = bf2f(proj[tg * NPROJ + PKG + dd]);
;       const float qt = qv * __expf(b) * 0.08838834764831845f, kt = kv * __expf(-b);
;       gq[(blk * 64 + t) * 128 + d] = f2bf(qt);
;       const bf16_t kb = f2bf(kt);
;       gk[(blk * 64 + t) * 128 + d] = kb;
;       if (tt & 1) ktp[tt >> 1] |= ((unsigned)kb) << 16; else ktp[tt >> 1] = kb;
;     }
	v_add_f32_e32 v63, v33, v74
	v_sub_f32_e32 v37, v61, v33
	v_add_f32_e32 v36, v63, v75
	v_sub_f32_e32 v38, v61, v63
	v_cndmask_b32_e64 v37, v37, v63, s[6:7]
	v_cndmask_b32_e64 v38, v38, v36, s[6:7]
	v_mul_f32_e32 v184, 0x3fb8aa3b, v37
	v_mul_f32_e32 v185, 0xbfb8aa3b, v37
	v_mul_f32_e32 v186, 0x3fb8aa3b, v38
	v_mul_f32_e32 v187, 0xbfb8aa3b, v38
	v_exp_f32_e32 v184, v184
	v_exp_f32_e32 v185, v185
	v_exp_f32_e32 v186, v186
	v_exp_f32_e32 v187, v187
	v_lshlrev_b32_e32 v188, 16, v106
	v_lshlrev_b32_e32 v189, 16, v154
	v_lshlrev_b32_e32 v190, 16, v107
	v_lshlrev_b32_e32 v191, 16, v155
	v_mul_f32_e32 v184, v184, v188
	v_mul_f32_e32 v185, v185, v189
	v_mul_f32_e32 v186, v186, v190
	v_mul_f32_e32 v187, v187, v191
	v_mul_f32_e32 v184, 0x3db504f3, v184
	v_mul_f32_e32 v186, 0x3db504f3, v186
	v_cvt_pk_bf16_f32 v188, v184, v186
	v_cvt_pk_bf16_f32 v133, v185, v187
	v_lshrrev_b32_e32 v190, 16, v188
	v_lshrrev_b32_e32 v191, 16, v133
	global_store_short v5, v188, s[24:25] offset:160
	global_store_short v5, v133, s[26:27] offset:160
	global_store_short v5, v190, s[24:25] offset:176
	global_store_short v5, v191, s[26:27] offset:176
	s_waitcnt vmcnt(56)
	v_add_f32_e32 v63, v36, v76
	v_sub_f32_e32 v40, v61, v36
	v_add_f32_e32 v39, v63, v77
	v_sub_f32_e32 v41, v61, v63
	v_cndmask_b32_e64 v40, v40, v63, s[6:7]
	v_cndmask_b32_e64 v41, v41, v39, s[6:7]
	v_mul_f32_e32 v42, 0x3fb8aa3b, v40
	v_mul_f32_e32 v43, 0xbfb8aa3b, v40
	v_mul_f32_e32 v44, 0x3fb8aa3b, v41
	v_mul_f32_e32 v45, 0xbfb8aa3b, v41
	v_exp_f32_e32 v42, v42
	v_exp_f32_e32 v43, v43
	v_exp_f32_e32 v44, v44
	v_exp_f32_e32 v45, v45
	v_lshlrev_b32_e32 v46, 16, v108
	v_lshlrev_b32_e32 v47, 16, v156
	v_lshlrev_b32_e32 v48, 16, v109
	v_lshlrev_b32_e32 v49, 16, v157
	v_mul_f32_e32 v42, v42, v46
	v_mul_f32_e32 v43, v43, v47
	v_mul_f32_e32 v44, v44, v48
	v_mul_f32_e32 v45, v45, v49
	v_mul_f32_e32 v42, 0x3db504f3, v42
	v_mul_f32_e32 v44, 0x3db504f3, v44
	v_cvt_pk_bf16_f32 v46, v42, v44
	v_cvt_pk_bf16_f32 v134, v43, v45
	v_lshrrev_b32_e32 v48, 16, v46
	v_lshrrev_b32_e32 v49, 16, v134
	global_store_short v5, v46, s[24:25] offset:192
	global_store_short v5, v134, s[26:27] offset:192
	global_store_short v5, v48, s[24:25] offset:208
	global_store_short v5, v49, s[26:27] offset:208
	s_waitcnt vmcnt(56)
	v_add_f32_e32 v63, v39, v78
	v_sub_f32_e32 v51, v61, v39
	v_add_f32_e32 v50, v63, v79
	v_sub_f32_e32 v52, v61, v63
	v_cndmask_b32_e64 v51, v51, v63, s[6:7]
	v_cndmask_b32_e64 v52, v52, v50, s[6:7]
	v_mul_f32_e32 v53, 0x3fb8aa3b, v51
	v_mul_f32_e32 v54, 0xbfb8aa3b, v51
	v_mul_f32_e32 v55, 0x3fb8aa3b, v52
	v_mul_f32_e32 v56, 0xbfb8aa3b, v52
	v_exp_f32_e32 v53, v53
	v_exp_f32_e32 v54, v54
	v_exp_f32_e32 v55, v55
	v_exp_f32_e32 v56, v56
	v_lshlrev_b32_e32 v57, 16, v110
	v_lshlrev_b32_e32 v58, 16, v158
	v_lshlrev_b32_e32 v59, 16, v111
	v_lshlrev_b32_e32 v60, 16, v159
	v_mul_f32_e32 v53, v53, v57
	v_mul_f32_e32 v54, v54, v58
	v_mul_f32_e32 v55, v55, v59
	v_mul_f32_e32 v56, v56, v60
	v_mul_f32_e32 v53, 0x3db504f3, v53
	v_mul_f32_e32 v55, 0x3db504f3, v55
	v_cvt_pk_bf16_f32 v57, v53, v55
	v_cvt_pk_bf16_f32 v135, v54, v56
	v_lshrrev_b32_e32 v59, 16, v57
	v_lshrrev_b32_e32 v60, 16, v135
	global_store_short v5, v57, s[24:25] offset:224
	global_store_short v5, v135, s[26:27] offset:224
	global_store_short v5, v59, s[24:25] offset:240
	global_store_short v5, v60, s[26:27] offset:240
	s_waitcnt vmcnt(56)
	v_add_f32_e32 v63, v50, v80
	v_sub_f32_e32 v34, v61, v50
	v_add_f32_e32 v33, v63, v81
	v_sub_f32_e32 v35, v61, v63
	v_cndmask_b32_e64 v34, v34, v63, s[6:7]
	v_cndmask_b32_e64 v35, v35, v33, s[6:7]
	v_mul_f32_e32 v176, 0x3fb8aa3b, v34
	v_mul_f32_e32 v177, 0xbfb8aa3b, v34
	v_mul_f32_e32 v178, 0x3fb8aa3b, v35
	v_mul_f32_e32 v179, 0xbfb8aa3b, v35
	v_exp_f32_e32 v176, v176
	v_exp_f32_e32 v177, v177
	v_exp_f32_e32 v178, v178
	v_exp_f32_e32 v179, v179
	v_lshlrev_b32_e32 v180, 16, v112
	v_lshlrev_b32_e32 v181, 16, v160
	v_lshlrev_b32_e32 v182, 16, v113
	v_lshlrev_b32_e32 v183, 16, v161
	v_mul_f32_e32 v176, v176, v180
	v_mul_f32_e32 v177, v177, v181
	v_mul_f32_e32 v178, v178, v182
	v_mul_f32_e32 v179, v179, v183
	v_mul_f32_e32 v176, 0x3db504f3, v176
	v_mul_f32_e32 v178, 0x3db504f3, v178
	v_cvt_pk_bf16_f32 v180, v176, v178
	v_cvt_pk_bf16_f32 v136, v177, v179
	v_lshrrev_b32_e32 v182, 16, v180
	v_lshrrev_b32_e32 v183, 16, v136
	global_store_short v5, v180, s[24:25] offset:256
	global_store_short v5, v136, s[26:27] offset:256
	global_store_short v5, v182, s[24:25] offset:272
	global_store_short v5, v183, s[26:27] offset:272
	s_waitcnt vmcnt(56)
	v_add_f32_e32 v63, v33, v82
	v_sub_f32_e32 v37, v61, v33
	v_add_f32_e32 v36, v63, v83
	v_sub_f32_e32 v38, v61, v63
	v_cndmask_b32_e64 v37, v37, v63, s[6:7]
	v_cndmask_b32_e64 v38, v38, v36, s[6:7]
	v_mul_f32_e32 v184, 0x3fb8aa3b, v37
	v_mul_f32_e32 v185, 0xbfb8aa3b, v37
	v_mul_f32_e32 v186, 0x3fb8aa3b, v38
	v_mul_f32_e32 v187, 0xbfb8aa3b, v38
	v_exp_f32_e32 v184, v184
	v_exp_f32_e32 v185, v185
	v_exp_f32_e32 v186, v186
	v_exp_f32_e32 v187, v187
	v_lshlrev_b32_e32 v188, 16, v114
	v_lshlrev_b32_e32 v189, 16, v162
	v_lshlrev_b32_e32 v190, 16, v115
	v_lshlrev_b32_e32 v191, 16, v163
	v_mul_f32_e32 v184, v184, v188
	v_mul_f32_e32 v185, v185, v189
	v_mul_f32_e32 v186, v186, v190
	v_mul_f32_e32 v187, v187, v191
	v_mul_f32_e32 v184, 0x3db504f3, v184
	v_mul_f32_e32 v186, 0x3db504f3, v186
	v_cvt_pk_bf16_f32 v188, v184, v186
	v_cvt_pk_bf16_f32 v137, v185, v187
	v_lshrrev_b32_e32 v190, 16, v188
	v_lshrrev_b32_e32 v191, 16, v137
	global_store_short v5, v188, s[24:25] offset:288
	global_store_short v5, v137, s[26:27] offset:288
	global_store_short v5, v190, s[24:25] offset:304
	global_store_short v5, v191, s[26:27] offset:304
	s_waitcnt vmcnt(56)
; DI float bf2f(bf16_t v) { return __uint_as_float(((unsigned)v) << 16); }
; DI bf16_t f2bf(float x) { return (bf16_t)(pk_bf16(x, 0.f) & 0xffffu); }
; DI float logsig16(float z) { return (fminf(z, 0.f) - __logf(1.f + __expf(-fabsf(z)))) * (1.f / 16.f); }
; DI void phase_gla_prep(const Params& p, int g, char* smem, int bid, int nb) {
;     ...
;     for (int tt = 0; tt < 32; ++tt) {
;       const int t = half * 32 + tt;
;       const float* l = lrs + t * 16; float z = bg;
; #pragma unroll
;       for (int r = 0; r < 16; ++r) z += l[r] * wg[r];
;       const float gv = logsig16(z);
;       const float b = dir ? (TOTAL - run) : (run + gv);
;       run += gv;
;       const size_t tg = (size_t)c * 64 + t;
;       const float qv = bf2f(proj[tg * NPROJ + PQG + dd]), kv = bf2f(proj[tg * NPROJ + PKG + dd]);
;       const float qt = qv * __expf(b) * 0.08838834764831845f, kt = kv * __expf(-b);
;       gq[(blk * 64 + t) * 128 + d] = f2bf(qt);
;       const bf16_t kb = f2bf(kt);
;       gk[(blk * 64 + t) * 128 + d] = kb;
;       if (tt & 1) ktp[tt >> 1] |= ((unsigned)kb) << 16; else ktp[tt >> 1] = kb;
;     }
;     bf16_t* kd = gkt + (blk * 128 + d) * 64 + half * 32;
; #pragma unroll
;     for (int q = 0; q < 4; ++q) { u32x4 v = {ktp[4 * q], ktp[4 * q + 1], ktp[4 * q + 2], ktp[4 * q + 3]}; *(u32x4*)(kd + 8 * q) = v; }
	v_add_f32_e32 v63, v36, v84
	v_sub_f32_e32 v40, v61, v36
	v_add_f32_e32 v39, v63, v85
	v_sub_f32_e32 v41, v61, v63
	v_cndmask_b32_e64 v40, v40, v63, s[6:7]
	v_cndmask_b32_e64 v41, v41, v39, s[6:7]
	v_mul_f32_e32 v42, 0x3fb8aa3b, v40
	v_mul_f32_e32 v43, 0xbfb8aa3b, v40
	v_mul_f32_e32 v44, 0x3fb8aa3b, v41
	v_mul_f32_e32 v45, 0xbfb8aa3b, v41
	v_exp_f32_e32 v42, v42
	v_exp_f32_e32 v43, v43
	v_exp_f32_e32 v44, v44
	v_exp_f32_e32 v45, v45
	v_lshlrev_b32_e32 v46, 16, v116
	v_lshlrev_b32_e32 v47, 16, v164
	v_lshlrev_b32_e32 v48, 16, v117
	v_lshlrev_b32_e32 v49, 16, v165
	v_mul_f32_e32 v42, v42, v46
	v_mul_f32_e32 v43, v43, v47
	v_mul_f32_e32 v44, v44, v48
	v_mul_f32_e32 v45, v45, v49
	v_mul_f32_e32 v42, 0x3db504f3, v42
	v_mul_f32_e32 v44, 0x3db504f3, v44
	v_cvt_pk_bf16_f32 v46, v42, v44
	v_cvt_pk_bf16_f32 v138, v43, v45
	v_lshrrev_b32_e32 v48, 16, v46
	v_lshrrev_b32_e32 v49, 16, v138
	global_store_short v5, v46, s[24:25] offset:320
	global_store_short v5, v138, s[26:27] offset:320
	global_store_short v5, v48, s[24:25] offset:336
	global_store_short v5, v49, s[26:27] offset:336
	s_waitcnt vmcnt(56)
	v_add_f32_e32 v63, v39, v86
	v_sub_f32_e32 v51, v61, v39
	v_add_f32_e32 v50, v63, v87
	v_sub_f32_e32 v52, v61, v63
	v_cndmask_b32_e64 v51, v51, v63, s[6:7]
	v_cndmask_b32_e64 v52, v52, v50, s[6:7]
	v_mul_f32_e32 v53, 0x3fb8aa3b, v51
	v_mul_f32_e32 v54, 0xbfb8aa3b, v51
	v_mul_f32_e32 v55, 0x3fb8aa3b, v52
	v_mul_f32_e32 v56, 0xbfb8aa3b, v52
	v_exp_f32_e32 v53, v53
	v_exp_f32_e32 v54, v54
	v_exp_f32_e32 v55, v55
	v_exp_f32_e32 v56, v56
	v_lshlrev_b32_e32 v57, 16, v118
	v_lshlrev_b32_e32 v58, 16, v166
	v_lshlrev_b32_e32 v59, 16, v119
	v_lshlrev_b32_e32 v60, 16, v167
	v_mul_f32_e32 v53, v53, v57
	v_mul_f32_e32 v54, v54, v58
	v_mul_f32_e32 v55, v55, v59
	v_mul_f32_e32 v56, v56, v60
	v_mul_f32_e32 v53, 0x3db504f3, v53
	v_mul_f32_e32 v55, 0x3db504f3, v55
	v_cvt_pk_bf16_f32 v57, v53, v55
	v_cvt_pk_bf16_f32 v139, v54, v56
	v_lshrrev_b32_e32 v59, 16, v57
	v_lshrrev_b32_e32 v60, 16, v139
	global_store_short v5, v57, s[24:25] offset:352
	global_store_short v5, v139, s[26:27] offset:352
	global_store_short v5, v59, s[24:25] offset:368
	global_store_short v5, v60, s[26:27] offset:368
	s_waitcnt vmcnt(56)
	v_add_f32_e32 v63, v50, v88
	v_sub_f32_e32 v34, v61, v50
	v_add_f32_e32 v33, v63, v89
	v_sub_f32_e32 v35, v61, v63
	v_cndmask_b32_e64 v34, v34, v63, s[6:7]
	v_cndmask_b32_e64 v35, v35, v33, s[6:7]
	v_mul_f32_e32 v176, 0x3fb8aa3b, v34
	v_mul_f32_e32 v177, 0xbfb8aa3b, v34
	v_mul_f32_e32 v178, 0x3fb8aa3b, v35
	v_mul_f32_e32 v179, 0xbfb8aa3b, v35
	v_exp_f32_e32 v176, v176
	v_exp_f32_e32 v177, v177
	v_exp_f32_e32 v178, v178
	v_exp_f32_e32 v179, v179
	v_lshlrev_b32_e32 v180, 16, v120
	v_lshlrev_b32_e32 v181, 16, v168
	v_lshlrev_b32_e32 v182, 16, v121
	v_lshlrev_b32_e32 v183, 16, v169
	v_mul_f32_e32 v176, v176, v180
	v_mul_f32_e32 v177, v177, v181
	v_mul_f32_e32 v178, v178, v182
	v_mul_f32_e32 v179, v179, v183
	v_mul_f32_e32 v176, 0x3db504f3, v176
	v_mul_f32_e32 v178, 0x3db504f3, v178
	v_cvt_pk_bf16_f32 v180, v176, v178
	v_cvt_pk_bf16_f32 v140, v177, v179
	v_lshrrev_b32_e32 v182, 16, v180
	v_lshrrev_b32_e32 v183, 16, v140
	global_store_short v5, v180, s[24:25] offset:384
	global_store_short v5, v140, s[26:27] offset:384
	global_store_short v5, v182, s[24:25] offset:400
	global_store_short v5, v183, s[26:27] offset:400
	s_waitcnt vmcnt(56)
	v_add_f32_e32 v63, v33, v90
	v_sub_f32_e32 v37, v61, v33
	v_add_f32_e32 v36, v63, v91
	v_sub_f32_e32 v38, v61, v63
	v_cndmask_b32_e64 v37, v37, v63, s[6:7]
	v_cndmask_b32_e64 v38, v38, v36, s[6:7]
	v_mul_f32_e32 v184, 0x3fb8aa3b, v37
	v_mul_f32_e32 v185, 0xbfb8aa3b, v37
	v_mul_f32_e32 v186, 0x3fb8aa3b, v38
	v_mul_f32_e32 v187, 0xbfb8aa3b, v38
	v_exp_f32_e32 v184, v184
	v_exp_f32_e32 v185, v185
	v_exp_f32_e32 v186, v186
	v_exp_f32_e32 v187, v187
	v_lshlrev_b32_e32 v188, 16, v122
	v_lshlrev_b32_e32 v189, 16, v170
	v_lshlrev_b32_e32 v190, 16, v123
	v_lshlrev_b32_e32 v191, 16, v171
	v_mul_f32_e32 v184, v184, v188
	v_mul_f32_e32 v185, v185, v189
	v_mul_f32_e32 v186, v186, v190
	v_mul_f32_e32 v187, v187, v191
	v_mul_f32_e32 v184, 0x3db504f3, v184
	v_mul_f32_e32 v186, 0x3db504f3, v186
	v_cvt_pk_bf16_f32 v188, v184, v186
	v_cvt_pk_bf16_f32 v141, v185, v187
	v_lshrrev_b32_e32 v190, 16, v188
	v_lshrrev_b32_e32 v191, 16, v141
	global_store_short v5, v188, s[24:25] offset:416
	global_store_short v5, v141, s[26:27] offset:416
	global_store_short v5, v190, s[24:25] offset:432
	global_store_short v5, v191, s[26:27] offset:432
	s_waitcnt vmcnt(56)
	v_add_f32_e32 v63, v36, v92
	v_sub_f32_e32 v40, v61, v36
	v_add_f32_e32 v39, v63, v93
	v_sub_f32_e32 v41, v61, v63
	v_cndmask_b32_e64 v40, v40, v63, s[6:7]
	v_cndmask_b32_e64 v41, v41, v39, s[6:7]
	v_mul_f32_e32 v42, 0x3fb8aa3b, v40
	v_mul_f32_e32 v43, 0xbfb8aa3b, v40
	v_mul_f32_e32 v44, 0x3fb8aa3b, v41
	v_mul_f32_e32 v45, 0xbfb8aa3b, v41
	v_exp_f32_e32 v42, v42
	v_exp_f32_e32 v43, v43
	v_exp_f32_e32 v44, v44
	v_exp_f32_e32 v45, v45
	v_lshlrev_b32_e32 v46, 16, v124
	v_lshlrev_b32_e32 v47, 16, v172
	v_lshlrev_b32_e32 v48, 16, v125
	v_lshlrev_b32_e32 v49, 16, v173
	v_mul_f32_e32 v42, v42, v46
	v_mul_f32_e32 v43, v43, v47
	v_mul_f32_e32 v44, v44, v48
	v_mul_f32_e32 v45, v45, v49
	v_mul_f32_e32 v42, 0x3db504f3, v42
	v_mul_f32_e32 v44, 0x3db504f3, v44
	v_cvt_pk_bf16_f32 v46, v42, v44
	v_cvt_pk_bf16_f32 v142, v43, v45
	v_lshrrev_b32_e32 v48, 16, v46
	v_lshrrev_b32_e32 v49, 16, v142
	global_store_short v5, v46, s[24:25] offset:448
	global_store_short v5, v142, s[26:27] offset:448
	global_store_short v5, v48, s[24:25] offset:464
	global_store_short v5, v49, s[26:27] offset:464
	s_waitcnt vmcnt(56)
	v_add_f32_e32 v63, v39, v94
	v_sub_f32_e32 v51, v61, v39
	v_add_f32_e32 v50, v63, v95
	v_sub_f32_e32 v52, v61, v63
	v_cndmask_b32_e64 v51, v51, v63, s[6:7]
	v_cndmask_b32_e64 v52, v52, v50, s[6:7]
	v_mul_f32_e32 v53, 0x3fb8aa3b, v51
	v_mul_f32_e32 v54, 0xbfb8aa3b, v51
	v_mul_f32_e32 v55, 0x3fb8aa3b, v52
	v_mul_f32_e32 v56, 0xbfb8aa3b, v52
	v_exp_f32_e32 v53, v53
	v_exp_f32_e32 v54, v54
	v_exp_f32_e32 v55, v55
	v_exp_f32_e32 v56, v56
	v_lshlrev_b32_e32 v57, 16, v126
	v_lshlrev_b32_e32 v58, 16, v174
	v_lshlrev_b32_e32 v59, 16, v127
	v_lshlrev_b32_e32 v60, 16, v175
	v_mul_f32_e32 v53, v53, v57
	v_mul_f32_e32 v54, v54, v58
	v_mul_f32_e32 v55, v55, v59
	v_mul_f32_e32 v56, v56, v60
	v_mul_f32_e32 v53, 0x3db504f3, v53
	v_mul_f32_e32 v55, 0x3db504f3, v55
	v_cvt_pk_bf16_f32 v57, v53, v55
	v_cvt_pk_bf16_f32 v143, v54, v56
	v_lshrrev_b32_e32 v59, 16, v57
	v_lshrrev_b32_e32 v60, 16, v143
	global_store_short v5, v57, s[24:25] offset:480
	global_store_short v5, v143, s[26:27] offset:480
	global_store_short v5, v59, s[24:25] offset:496
	global_store_short v5, v60, s[26:27] offset:496
	s_waitcnt vmcnt(56)
	global_store_dwordx4 v10, v[128:131], s[28:29]
	global_store_dwordx4 v10, v[132:135], s[28:29] offset:512
	global_store_dwordx4 v10, v[136:139], s[28:29] offset:1024
	global_store_dwordx4 v10, v[140:143], s[28:29] offset:1536
	s_cmp_lg_u32 s8, 0
	s_cbranch_scc1 .Lgp_noge
; DI void phase_gla_prep(const Params& p, int g, char* smem, int bid, int nb) {
;     ...
;     if (half == 0) ge[blk * 128 + d] = __expf(TOTAL);
	v_mul_f32_e32 v33, 0x3fb8aa3b, v61
	v_exp_f32_e32 v33, v33
	s_nop 0
	global_store_dword v9, v33, s[30:31]
